# v20
# baseline (speedup 1.0000x reference)
; #define PG8_STAGE(bufoff, gbase, voff) do { const __amdgpu_buffer_rsrc_t _rs = __builtin_amdgcn_make_buffer_rsrc((void*)(gbase), 0, 0x7fffffff, 0x00020000); _Pragma("unroll") for (int _i = 0; _i < 2; ++_i) \
;         __builtin_amdgcn_raw_ptr_buffer_load_lds(_rs, (LAS unsigned*)(lds + (bufoff) + ldsw + _i * 8192), 16, (int)(voff)[_i], 0, 0, 0); } while (0)
; #define PG8_WAIT_V(n) asm volatile("s_waitcnt vmcnt(" #n ")" ::: "memory")
; #define PG8_WAIT_L(n) asm volatile("s_waitcnt lgkmcnt(" #n ")" ::: "memory")
; #define PG8_BAR __builtin_amdgcn_s_barrier()
; #define PG8_SCHED __builtin_amdgcn_sched_barrier(0)
; template <class Epi, class Sched, bool F8 = false>
; __device__ __forceinline__ void gemm_phase(LAS unsigned char* lds, const int lda, const int ldb, const Sched& S, const Epi& E) {
;     ...
;             const char* a1 = cA + (size_t)(t + 1) * kstep;
;             const char* a2 = last ? nA : cA + (size_t)(t + 2) * kstep; const char* b2 = last ? nB : cB + (size_t)(t + 2) * kstepB;
;             const char* a3 = a2 + kstep; const char* b3 = b2 + kstepB;
;     ...
;             PG8_LDB(B0, 0, 0); PG8_LDB(B1, 0, 1); PG8_SCHED; PG8_LDA(At, 0, 0); PG8_STAGE(PG8_SA(1, 1), a1 + hstepA, voffA);
;             PG8_WAIT_V(8); PG8_WAIT_L(0); PG8_BAR; PG8_MMA(0, 0, At, B0); PG8_MMA(0, 1, At, B1); PG8_BAR; PG8_SCHED;
;             PG8_LDA(At, 0, 1); PG8_STAGE(PG8_SB(0, 0), b2, voffB); PG8_STAGE(PG8_SB(0, 1), b2 + hstepB, voffB); PG8_STAGE(PG8_SA(0, 0), a2, voffA);
;             PG8_WAIT_V(8); PG8_WAIT_L(0); PG8_BAR; PG8_MMA(1, 0, At, B0); PG8_MMA(1, 1, At, B1); PG8_BAR; PG8_SCHED;
.LBB0_116:
	s_add_u32 s16, s63, 0xfff00080
	s_addc_u32 s17, s67, -1
	s_cmp_eq_u32 s69, 60
	s_cselect_b32 s28, s70, s16
	s_cselect_b32 s23, s71, s17
	s_cselect_b32 s22, s73, s62
	s_cselect_b32 s24, s72, s7
	s_add_u32 s20, s28, 0x80
	s_addc_u32 s21, s23, 0
	s_and_b32 s17, s67, 0xffff
	s_mov_b32 s16, s63
	s_mov_b32 m0, s93
	s_nop 0
	buffer_load_dwordx4 v136, s[16:19], 0 offen lds
	s_mov_b32 m0, s94
	s_nop 0
	buffer_load_dwordx4 v138, s[16:19], 0 offen lds
	ds_read_b128 v[132:135], v140
	ds_read_b128 v[146:149], v140 offset:1024
	ds_read_b128 v[150:153], v140 offset:2048
	ds_read_b128 v[154:157], v140 offset:3072
	ds_read_b128 v[158:161], v141
	ds_read_b128 v[162:165], v141 offset:1024
	ds_read_b128 v[166:169], v141 offset:2048
	ds_read_b128 v[174:177], v141 offset:3072
	ds_read_b128 v[178:181], v142
	ds_read_b128 v[182:185], v142 offset:1024
	ds_read_b128 v[186:189], v142 offset:2048
	ds_read_b128 v[190:193], v142 offset:3072
	ds_read_b128 v[194:197], v142 offset:4096
	ds_read_b128 v[198:201], v142 offset:5120
	ds_read_b128 v[202:205], v142 offset:6144
	ds_read_b128 v[206:209], v142 offset:7168
	s_waitcnt vmcnt(8)
	s_waitcnt lgkmcnt(0)
	s_barrier
	s_setprio 1
	v_mfma_f32_16x16x32_bf16 v[124:127], v[132:135], v[178:181], v[124:127]
	v_mfma_f32_16x16x32_bf16 v[120:123], v[150:153], v[178:181], v[120:123]
	v_mfma_f32_16x16x32_bf16 v[108:111], v[132:135], v[186:189], v[108:111]
	v_mfma_f32_16x16x32_bf16 v[104:107], v[150:153], v[186:189], v[104:107]
	v_mfma_f32_16x16x32_bf16 v[92:95], v[132:135], v[194:197], v[92:95]
	v_mfma_f32_16x16x32_bf16 v[88:91], v[150:153], v[194:197], v[88:91]
	v_mfma_f32_16x16x32_bf16 v[76:79], v[132:135], v[202:205], v[76:79]
	v_mfma_f32_16x16x32_bf16 v[72:75], v[150:153], v[202:205], v[72:75]
	v_mfma_f32_16x16x32_bf16 v[124:127], v[146:149], v[182:185], v[124:127]
	v_mfma_f32_16x16x32_bf16 v[120:123], v[154:157], v[182:185], v[120:123]
	v_mfma_f32_16x16x32_bf16 v[108:111], v[146:149], v[190:193], v[108:111]
	v_mfma_f32_16x16x32_bf16 v[104:107], v[154:157], v[190:193], v[104:107]
	v_mfma_f32_16x16x32_bf16 v[92:95], v[146:149], v[198:201], v[92:95]
	v_mfma_f32_16x16x32_bf16 v[88:91], v[154:157], v[198:201], v[88:91]
	v_mfma_f32_16x16x32_bf16 v[76:79], v[146:149], v[206:209], v[76:79]
	v_mfma_f32_16x16x32_bf16 v[72:75], v[154:157], v[206:209], v[72:75]
	s_setprio 0
	s_setprio 1
	v_mfma_f32_16x16x32_bf16 v[116:119], v[158:161], v[178:181], v[116:119]
	v_mfma_f32_16x16x32_bf16 v[112:115], v[166:169], v[178:181], v[112:115]
	v_mfma_f32_16x16x32_bf16 v[100:103], v[158:161], v[186:189], v[100:103]
	v_mfma_f32_16x16x32_bf16 v[96:99], v[166:169], v[186:189], v[96:99]
	v_mfma_f32_16x16x32_bf16 v[84:87], v[158:161], v[194:197], v[84:87]
	v_mfma_f32_16x16x32_bf16 v[80:83], v[166:169], v[194:197], v[80:83]
	v_mfma_f32_16x16x32_bf16 v[68:71], v[158:161], v[202:205], v[68:71]
	v_mfma_f32_16x16x32_bf16 v[64:67], v[166:169], v[202:205], v[64:67]
	v_mfma_f32_16x16x32_bf16 v[116:119], v[162:165], v[182:185], v[116:119]
	v_mfma_f32_16x16x32_bf16 v[112:115], v[174:177], v[182:185], v[112:115]
	v_mfma_f32_16x16x32_bf16 v[100:103], v[162:165], v[190:193], v[100:103]
	v_mfma_f32_16x16x32_bf16 v[96:99], v[174:177], v[190:193], v[96:99]
	v_mfma_f32_16x16x32_bf16 v[84:87], v[162:165], v[198:201], v[84:87]
	v_mfma_f32_16x16x32_bf16 v[80:83], v[174:177], v[198:201], v[80:83]
	v_mfma_f32_16x16x32_bf16 v[68:71], v[162:165], v[206:209], v[68:71]
	v_mfma_f32_16x16x32_bf16 v[64:67], v[174:177], v[206:209], v[64:67]
	s_setprio 0
	s_barrier
	s_and_b32 s25, s22, 0xffff
	s_mov_b32 m0, s8
	s_mov_b32 s26, s18
	s_mov_b32 s27, s19
	s_add_u32 s16, s24, 0x4000
	buffer_load_dwordx4 v137, s[24:27], 0 offen lds
	s_mov_b32 m0, s9
	s_addc_u32 s17, s22, 0
	buffer_load_dwordx4 v139, s[24:27], 0 offen lds
	s_and_b32 s17, s17, 0xffff
	s_mov_b32 m0, s76
	s_and_b32 s29, s23, 0xffff
	buffer_load_dwordx4 v137, s[16:19], 0 offen lds
	s_mov_b32 m0, s79
	s_mov_b32 s30, s18
	buffer_load_dwordx4 v139, s[16:19], 0 offen lds
	s_mov_b32 s31, s19
	s_mov_b32 m0, s3
	s_nop 0
	buffer_load_dwordx4 v136, s[28:31], 0 offen lds
	s_mov_b32 m0, s80
	s_nop 0
	buffer_load_dwordx4 v138, s[28:31], 0 offen lds
	ds_read_b128 v[178:181], v142 offset:16384
	ds_read_b128 v[182:185], v142 offset:17408
	ds_read_b128 v[186:189], v142 offset:18432
	ds_read_b128 v[190:193], v142 offset:19456
	ds_read_b128 v[194:197], v142 offset:20480
	ds_read_b128 v[198:201], v142 offset:21504
	ds_read_b128 v[202:205], v142 offset:22528
	ds_read_b128 v[206:209], v142 offset:23552
	s_waitcnt vmcnt(8)
	s_waitcnt lgkmcnt(0)
	s_barrier
; #define PG8_STAGE(bufoff, gbase, voff) do { const __amdgpu_buffer_rsrc_t _rs = __builtin_amdgcn_make_buffer_rsrc((void*)(gbase), 0, 0x7fffffff, 0x00020000); _Pragma("unroll") for (int _i = 0; _i < 2; ++_i) \
;         __builtin_amdgcn_raw_ptr_buffer_load_lds(_rs, (LAS unsigned*)(lds + (bufoff) + ldsw + _i * 8192), 16, (int)(voff)[_i], 0, 0, 0); } while (0)
; #define PG8_WAIT_V(n) asm volatile("s_waitcnt vmcnt(" #n ")" ::: "memory")
; #define PG8_WAIT_L(n) asm volatile("s_waitcnt lgkmcnt(" #n ")" ::: "memory")
; #define PG8_BAR __builtin_amdgcn_s_barrier()
; #define PG8_SCHED __builtin_amdgcn_sched_barrier(0)
; template <class Epi, class Sched, bool F8 = false>
; __device__ __forceinline__ void gemm_phase(LAS unsigned char* lds, const int lda, const int ldb, const Sched& S, const Epi& E) {
;     ...
;             PG8_WAIT_V(8); PG8_WAIT_L(0); PG8_BAR; PG8_MMA(1, 0, At, B0); PG8_MMA(1, 1, At, B1); PG8_BAR; PG8_SCHED;
;             PG8_LDB(B0, 1, 0); PG8_LDB(B1, 1, 1); PG8_SCHED; PG8_LDA(At, 1, 0); PG8_STAGE(PG8_SA(0, 1), a2 + hstepA, voffA);
;             PG8_WAIT_V(8); PG8_WAIT_L(0); PG8_BAR; PG8_MMA(0, 0, At, B0); PG8_MMA(0, 1, At, B1); PG8_BAR; PG8_SCHED;
	s_setprio 1
	v_mfma_f32_16x16x32_bf16 v[60:63], v[132:135], v[178:181], v[60:63]
	v_mfma_f32_16x16x32_bf16 v[56:59], v[150:153], v[178:181], v[56:59]
	v_mfma_f32_16x16x32_bf16 v[44:47], v[132:135], v[186:189], v[44:47]
	v_mfma_f32_16x16x32_bf16 v[40:43], v[150:153], v[186:189], v[40:43]
	v_mfma_f32_16x16x32_bf16 v[28:31], v[132:135], v[194:197], v[28:31]
	v_mfma_f32_16x16x32_bf16 v[24:27], v[150:153], v[194:197], v[24:27]
	v_mfma_f32_16x16x32_bf16 v[12:15], v[132:135], v[202:205], v[12:15]
	v_mfma_f32_16x16x32_bf16 v[8:11], v[150:153], v[202:205], v[8:11]
	v_mfma_f32_16x16x32_bf16 v[60:63], v[146:149], v[182:185], v[60:63]
	v_mfma_f32_16x16x32_bf16 v[56:59], v[154:157], v[182:185], v[56:59]
	v_mfma_f32_16x16x32_bf16 v[44:47], v[146:149], v[190:193], v[44:47]
	v_mfma_f32_16x16x32_bf16 v[40:43], v[154:157], v[190:193], v[40:43]
	v_mfma_f32_16x16x32_bf16 v[28:31], v[146:149], v[198:201], v[28:31]
	v_mfma_f32_16x16x32_bf16 v[24:27], v[154:157], v[198:201], v[24:27]
	v_mfma_f32_16x16x32_bf16 v[12:15], v[146:149], v[206:209], v[12:15]
	v_mfma_f32_16x16x32_bf16 v[8:11], v[154:157], v[206:209], v[8:11]
	s_setprio 0
	s_setprio 1
	v_mfma_f32_16x16x32_bf16 v[52:55], v[158:161], v[178:181], v[52:55]
	v_mfma_f32_16x16x32_bf16 v[48:51], v[166:169], v[178:181], v[48:51]
	v_mfma_f32_16x16x32_bf16 v[36:39], v[158:161], v[186:189], v[36:39]
	v_mfma_f32_16x16x32_bf16 v[32:35], v[166:169], v[186:189], v[32:35]
	v_mfma_f32_16x16x32_bf16 v[20:23], v[158:161], v[194:197], v[20:23]
	v_mfma_f32_16x16x32_bf16 v[16:19], v[166:169], v[194:197], v[16:19]
	v_mfma_f32_16x16x32_bf16 v[4:7], v[158:161], v[202:205], v[4:7]
	v_mfma_f32_16x16x32_bf16 v[0:3], v[166:169], v[202:205], v[0:3]
	v_mfma_f32_16x16x32_bf16 v[52:55], v[162:165], v[182:185], v[52:55]
	v_mfma_f32_16x16x32_bf16 v[48:51], v[174:177], v[182:185], v[48:51]
	v_mfma_f32_16x16x32_bf16 v[36:39], v[162:165], v[190:193], v[36:39]
	v_mfma_f32_16x16x32_bf16 v[32:35], v[174:177], v[190:193], v[32:35]
	v_mfma_f32_16x16x32_bf16 v[20:23], v[162:165], v[198:201], v[20:23]
	v_mfma_f32_16x16x32_bf16 v[16:19], v[174:177], v[198:201], v[16:19]
	v_mfma_f32_16x16x32_bf16 v[4:7], v[162:165], v[206:209], v[4:7]
	v_mfma_f32_16x16x32_bf16 v[0:3], v[174:177], v[206:209], v[0:3]
	s_setprio 0
	s_barrier
	s_add_u32 s16, s28, 0x100000
	s_addc_u32 s17, s23, 0
	s_and_b32 s17, s17, 0xffff
	s_mov_b32 m0, s81
	s_nop 0
	buffer_load_dwordx4 v136, s[16:19], 0 offen lds
	s_mov_b32 m0, s82
	s_nop 0
	buffer_load_dwordx4 v138, s[16:19], 0 offen lds
	ds_read_b128 v[132:135], v143
	ds_read_b128 v[146:149], v143 offset:1024
	ds_read_b128 v[150:153], v143 offset:2048
	ds_read_b128 v[154:157], v143 offset:3072
	ds_read_b128 v[158:161], v144
	ds_read_b128 v[162:165], v144 offset:1024
	ds_read_b128 v[166:169], v144 offset:2048
	ds_read_b128 v[174:177], v144 offset:3072
	ds_read_b128 v[178:181], v142 offset:32768
	ds_read_b128 v[182:185], v142 offset:33792
	ds_read_b128 v[186:189], v142 offset:34816
	ds_read_b128 v[190:193], v142 offset:35840
	ds_read_b128 v[194:197], v142 offset:36864
	ds_read_b128 v[198:201], v142 offset:37888
	ds_read_b128 v[202:205], v142 offset:38912
	ds_read_b128 v[206:209], v142 offset:39936
	s_waitcnt vmcnt(8)
	s_waitcnt lgkmcnt(0)
	s_barrier
	s_setprio 1
	v_mfma_f32_16x16x32_bf16 v[124:127], v[132:135], v[178:181], v[124:127]
	v_mfma_f32_16x16x32_bf16 v[120:123], v[150:153], v[178:181], v[120:123]
	v_mfma_f32_16x16x32_bf16 v[108:111], v[132:135], v[186:189], v[108:111]
	v_mfma_f32_16x16x32_bf16 v[104:107], v[150:153], v[186:189], v[104:107]
	v_mfma_f32_16x16x32_bf16 v[92:95], v[132:135], v[194:197], v[92:95]
	v_mfma_f32_16x16x32_bf16 v[88:91], v[150:153], v[194:197], v[88:91]
	v_mfma_f32_16x16x32_bf16 v[76:79], v[132:135], v[202:205], v[76:79]
	v_mfma_f32_16x16x32_bf16 v[72:75], v[150:153], v[202:205], v[72:75]
	v_mfma_f32_16x16x32_bf16 v[124:127], v[146:149], v[182:185], v[124:127]
	v_mfma_f32_16x16x32_bf16 v[120:123], v[154:157], v[182:185], v[120:123]
	v_mfma_f32_16x16x32_bf16 v[108:111], v[146:149], v[190:193], v[108:111]
	v_mfma_f32_16x16x32_bf16 v[104:107], v[154:157], v[190:193], v[104:107]
	v_mfma_f32_16x16x32_bf16 v[92:95], v[146:149], v[198:201], v[92:95]
	v_mfma_f32_16x16x32_bf16 v[88:91], v[154:157], v[198:201], v[88:91]
	v_mfma_f32_16x16x32_bf16 v[76:79], v[146:149], v[206:209], v[76:79]
	v_mfma_f32_16x16x32_bf16 v[72:75], v[154:157], v[206:209], v[72:75]
	s_setprio 0
	s_setprio 1
	v_mfma_f32_16x16x32_bf16 v[116:119], v[158:161], v[178:181], v[116:119]
	v_mfma_f32_16x16x32_bf16 v[112:115], v[166:169], v[178:181], v[112:115]
	v_mfma_f32_16x16x32_bf16 v[100:103], v[158:161], v[186:189], v[100:103]
	v_mfma_f32_16x16x32_bf16 v[96:99], v[166:169], v[186:189], v[96:99]
	v_mfma_f32_16x16x32_bf16 v[84:87], v[158:161], v[194:197], v[84:87]
	v_mfma_f32_16x16x32_bf16 v[80:83], v[166:169], v[194:197], v[80:83]
	v_mfma_f32_16x16x32_bf16 v[68:71], v[158:161], v[202:205], v[68:71]
	v_mfma_f32_16x16x32_bf16 v[64:67], v[166:169], v[202:205], v[64:67]
	v_mfma_f32_16x16x32_bf16 v[116:119], v[162:165], v[182:185], v[116:119]
	v_mfma_f32_16x16x32_bf16 v[112:115], v[174:177], v[182:185], v[112:115]
	v_mfma_f32_16x16x32_bf16 v[100:103], v[162:165], v[190:193], v[100:103]
	v_mfma_f32_16x16x32_bf16 v[96:99], v[174:177], v[190:193], v[96:99]
	v_mfma_f32_16x16x32_bf16 v[84:87], v[162:165], v[198:201], v[84:87]
	v_mfma_f32_16x16x32_bf16 v[80:83], v[174:177], v[198:201], v[80:83]
	v_mfma_f32_16x16x32_bf16 v[68:71], v[162:165], v[206:209], v[68:71]
	v_mfma_f32_16x16x32_bf16 v[64:67], v[174:177], v[206:209], v[64:67]
	s_setprio 0
	s_barrier
; #define PG8_STAGE(bufoff, gbase, voff) do { const __amdgpu_buffer_rsrc_t _rs = __builtin_amdgcn_make_buffer_rsrc((void*)(gbase), 0, 0x7fffffff, 0x00020000); _Pragma("unroll") for (int _i = 0; _i < 2; ++_i) \
;         __builtin_amdgcn_raw_ptr_buffer_load_lds(_rs, (LAS unsigned*)(lds + (bufoff) + ldsw + _i * 8192), 16, (int)(voff)[_i], 0, 0, 0); } while (0)
; #define PG8_WAIT_V(n) asm volatile("s_waitcnt vmcnt(" #n ")" ::: "memory")
; #define PG8_WAIT_L(n) asm volatile("s_waitcnt lgkmcnt(" #n ")" ::: "memory")
; #define PG8_BAR __builtin_amdgcn_s_barrier()
; #define PG8_SCHED __builtin_amdgcn_sched_barrier(0)
; template <class Epi, class Sched, bool F8 = false>
; __device__ __forceinline__ void gemm_phase(LAS unsigned char* lds, const int lda, const int ldb, const Sched& S, const Epi& E) {
;     ...
;             PG8_LDA(At, 1, 1); PG8_STAGE(PG8_SB(1, 0), b3, voffB); PG8_STAGE(PG8_SB(1, 1), b3 + hstepB, voffB); PG8_STAGE(PG8_SA(1, 0), a3, voffA);
;             PG8_WAIT_V(8); PG8_WAIT_L(0); PG8_BAR; PG8_MMA(1, 0, At, B0); PG8_MMA(1, 1, At, B1); PG8_BAR; PG8_SCHED;
	s_add_u32 s16, s24, 0x8000
	s_addc_u32 s17, s22, 0
	s_mov_b32 m0, s87
	s_and_b32 s17, s17, 0xffff
	buffer_load_dwordx4 v137, s[16:19], 0 offen lds
	s_mov_b32 m0, s88
	s_mov_b32 s23, s19
	buffer_load_dwordx4 v139, s[16:19], 0 offen lds
	s_add_u32 s16, s24, 0xc000
	s_addc_u32 s17, s22, 0
	s_and_b32 s17, s17, 0xffff
	s_mov_b32 m0, s91
	s_and_b32 s21, s21, 0xffff
	buffer_load_dwordx4 v137, s[16:19], 0 offen lds
	s_mov_b32 m0, s92
	s_mov_b32 s22, s18
	buffer_load_dwordx4 v139, s[16:19], 0 offen lds
	s_mov_b32 m0, s89
	s_nop 0
	buffer_load_dwordx4 v136, s[20:23], 0 offen lds
	s_mov_b32 m0, s90
	s_nop 0
	buffer_load_dwordx4 v138, s[20:23], 0 offen lds
	ds_read_b128 v[178:181], v142 offset:49152
	ds_read_b128 v[182:185], v142 offset:50176
	ds_read_b128 v[186:189], v142 offset:51200
	ds_read_b128 v[190:193], v142 offset:52224
	ds_read_b128 v[194:197], v142 offset:53248
	ds_read_b128 v[198:201], v142 offset:54272
	ds_read_b128 v[202:205], v142 offset:55296
	ds_read_b128 v[206:209], v142 offset:56320
	s_waitcnt vmcnt(8)
	s_waitcnt lgkmcnt(0)
	s_barrier
	s_setprio 1
	v_mfma_f32_16x16x32_bf16 v[60:63], v[132:135], v[178:181], v[60:63]
	v_mfma_f32_16x16x32_bf16 v[56:59], v[150:153], v[178:181], v[56:59]
	v_mfma_f32_16x16x32_bf16 v[44:47], v[132:135], v[186:189], v[44:47]
	v_mfma_f32_16x16x32_bf16 v[40:43], v[150:153], v[186:189], v[40:43]
	v_mfma_f32_16x16x32_bf16 v[28:31], v[132:135], v[194:197], v[28:31]
	v_mfma_f32_16x16x32_bf16 v[24:27], v[150:153], v[194:197], v[24:27]
	v_mfma_f32_16x16x32_bf16 v[12:15], v[132:135], v[202:205], v[12:15]
	v_mfma_f32_16x16x32_bf16 v[8:11], v[150:153], v[202:205], v[8:11]
	v_mfma_f32_16x16x32_bf16 v[60:63], v[146:149], v[182:185], v[60:63]
	v_mfma_f32_16x16x32_bf16 v[56:59], v[154:157], v[182:185], v[56:59]
	v_mfma_f32_16x16x32_bf16 v[44:47], v[146:149], v[190:193], v[44:47]
	v_mfma_f32_16x16x32_bf16 v[40:43], v[154:157], v[190:193], v[40:43]
	v_mfma_f32_16x16x32_bf16 v[28:31], v[146:149], v[198:201], v[28:31]
	v_mfma_f32_16x16x32_bf16 v[24:27], v[154:157], v[198:201], v[24:27]
	v_mfma_f32_16x16x32_bf16 v[12:15], v[146:149], v[206:209], v[12:15]
	v_mfma_f32_16x16x32_bf16 v[8:11], v[154:157], v[206:209], v[8:11]
	s_setprio 0
	s_setprio 1
	v_mfma_f32_16x16x32_bf16 v[52:55], v[158:161], v[178:181], v[52:55]
	v_mfma_f32_16x16x32_bf16 v[48:51], v[166:169], v[178:181], v[48:51]
	v_mfma_f32_16x16x32_bf16 v[36:39], v[158:161], v[186:189], v[36:39]
	v_mfma_f32_16x16x32_bf16 v[32:35], v[166:169], v[186:189], v[32:35]
	v_mfma_f32_16x16x32_bf16 v[20:23], v[158:161], v[194:197], v[20:23]
	v_mfma_f32_16x16x32_bf16 v[16:19], v[166:169], v[194:197], v[16:19]
	v_mfma_f32_16x16x32_bf16 v[4:7], v[158:161], v[202:205], v[4:7]
	v_mfma_f32_16x16x32_bf16 v[0:3], v[166:169], v[202:205], v[0:3]
	v_mfma_f32_16x16x32_bf16 v[52:55], v[162:165], v[182:185], v[52:55]
	v_mfma_f32_16x16x32_bf16 v[48:51], v[174:177], v[182:185], v[48:51]
	v_mfma_f32_16x16x32_bf16 v[36:39], v[162:165], v[190:193], v[36:39]
	v_mfma_f32_16x16x32_bf16 v[32:35], v[174:177], v[190:193], v[32:35]
	v_mfma_f32_16x16x32_bf16 v[20:23], v[162:165], v[198:201], v[20:23]
	v_mfma_f32_16x16x32_bf16 v[16:19], v[174:177], v[198:201], v[16:19]
	v_mfma_f32_16x16x32_bf16 v[4:7], v[162:165], v[206:209], v[4:7]
	v_mfma_f32_16x16x32_bf16 v[0:3], v[174:177], v[206:209], v[0:3]
	s_setprio 0
	s_barrier
	s_add_i32 s69, s69, 2
	s_add_u32 s7, s7, 0x10000
	s_addc_u32 s62, s62, 0
	s_add_u32 s63, s63, 0x100
	s_addc_u32 s67, s67, 0
	s_cmp_gt_u32 s69, 61
	s_cbranch_scc0 .LBB0_116
	s_and_b64 vcc, exec, s[38:39]
	s_cbranch_vccz .LBB0_119
	s_barrier

; #define PG8_STAGE(bufoff, gbase, voff) do { const __amdgpu_buffer_rsrc_t _rs = __builtin_amdgcn_make_buffer_rsrc((void*)(gbase), 0, 0x7fffffff, 0x00020000); _Pragma("unroll") for (int _i = 0; _i < 2; ++_i) \
;         __builtin_amdgcn_raw_ptr_buffer_load_lds(_rs, (LAS unsigned*)(lds + (bufoff) + ldsw + _i * 8192), 16, (int)(voff)[_i], 0, 0, 0); } while (0)
; #define PG8_WAIT_V(n) asm volatile("s_waitcnt vmcnt(" #n ")" ::: "memory")
; #define PG8_WAIT_L(n) asm volatile("s_waitcnt lgkmcnt(" #n ")" ::: "memory")
; #define PG8_BAR __builtin_amdgcn_s_barrier()
; #define PG8_SCHED __builtin_amdgcn_sched_barrier(0)
; template <class Epi, class Sched, bool F8 = false>
; __device__ __forceinline__ void gemm_phase(LAS unsigned char* lds, const int lda, const int ldb, const Sched& S, const Epi& E) {
;     ...
;             const char* a1 = cA + (size_t)(t + 1) * kstep;
;             const char* a2 = last ? nA : cA + (size_t)(t + 2) * kstep; const char* b2 = last ? nB : cB + (size_t)(t + 2) * kstepB;
;             const char* a3 = a2 + kstep; const char* b3 = b2 + kstepB;
;     ...
;             PG8_LDB(B0, 0, 0); PG8_LDB(B1, 0, 1); PG8_SCHED; PG8_LDA(At, 0, 0); PG8_STAGE(PG8_SA(1, 1), a1 + hstepA, voffA);
;             PG8_WAIT_V(8); PG8_WAIT_L(0); PG8_BAR; PG8_MMA(0, 0, At, B0); PG8_MMA(0, 1, At, B1); PG8_BAR; PG8_SCHED;
;             PG8_LDA(At, 0, 1); PG8_STAGE(PG8_SB(0, 0), b2, voffB); PG8_STAGE(PG8_SB(0, 1), b2 + hstepB, voffB); PG8_STAGE(PG8_SA(0, 0), a2, voffA);
;             PG8_WAIT_V(8); PG8_WAIT_L(0); PG8_BAR; PG8_MMA(1, 0, At, B0); PG8_MMA(1, 1, At, B1); PG8_BAR; PG8_SCHED;
.LBB0_174:
	s_add_u32 s16, s63, 0xfff80080
	s_addc_u32 s17, s67, -1
	s_cmp_eq_u32 s69, 28
	s_cselect_b32 s28, s70, s16
	s_cselect_b32 s23, s71, s17
	s_cselect_b32 s22, s73, s62
	s_cselect_b32 s24, s72, s7
	s_add_u32 s20, s28, 0x80
	s_addc_u32 s21, s23, 0
	s_and_b32 s17, s67, 0xffff
	s_mov_b32 s16, s63
	s_mov_b32 m0, s96
	s_nop 0
	buffer_load_dwordx4 v136, s[16:19], 0 offen lds
	s_mov_b32 m0, s97
	s_nop 0
	buffer_load_dwordx4 v138, s[16:19], 0 offen lds
	ds_read_b128 v[146:149], v140
	ds_read_b128 v[150:153], v140 offset:1024
	ds_read_b128 v[154:157], v140 offset:2048
	ds_read_b128 v[158:161], v140 offset:3072
	ds_read_b128 v[162:165], v141
	ds_read_b128 v[166:169], v141 offset:1024
	ds_read_b128 v[174:177], v141 offset:2048
	ds_read_b128 v[178:181], v141 offset:3072
	ds_read_b128 v[182:185], v142
	ds_read_b128 v[186:189], v142 offset:1024
	ds_read_b128 v[190:193], v142 offset:2048
	ds_read_b128 v[194:197], v142 offset:3072
	ds_read_b128 v[198:201], v142 offset:4096
	ds_read_b128 v[202:205], v142 offset:5120
	ds_read_b128 v[206:209], v142 offset:6144
	ds_read_b128 v[210:213], v142 offset:7168
	s_waitcnt vmcnt(8)
	s_waitcnt lgkmcnt(0)
	s_barrier
	s_setprio 1
	v_mfma_scale_f32_16x16x128_f8f6f4 v[124:127], v[146:153], v[182:189], v[124:127], v143, v143 op_sel_hi:[0,0,0]
	v_mfma_scale_f32_16x16x128_f8f6f4 v[120:123], v[154:161], v[182:189], v[120:123], v143, v143 op_sel_hi:[0,0,0]
	v_mfma_scale_f32_16x16x128_f8f6f4 v[108:111], v[146:153], v[190:197], v[108:111], v143, v143 op_sel_hi:[0,0,0]
	v_mfma_scale_f32_16x16x128_f8f6f4 v[104:107], v[154:161], v[190:197], v[104:107], v143, v143 op_sel_hi:[0,0,0]
	v_mfma_scale_f32_16x16x128_f8f6f4 v[132:135], v[146:153], v[198:205], v[92:95], v143, v143 op_sel_hi:[0,0,0]
	v_mfma_scale_f32_16x16x128_f8f6f4 v[214:217], v[154:161], v[198:205], v[88:91], v143, v143 op_sel_hi:[0,0,0]
	v_mfma_scale_f32_16x16x128_f8f6f4 v[218:221], v[146:153], v[206:213], v[76:79], v143, v143 op_sel_hi:[0,0,0]
	v_mfma_scale_f32_16x16x128_f8f6f4 v[222:225], v[154:161], v[206:213], v[72:75], v143, v143 op_sel_hi:[0,0,0]
	s_setprio 0
	s_setprio 1
	v_mfma_scale_f32_16x16x128_f8f6f4 v[116:119], v[162:169], v[182:189], v[116:119], v143, v143 op_sel_hi:[0,0,0]
	v_mfma_scale_f32_16x16x128_f8f6f4 v[112:115], v[174:181], v[182:189], v[112:115], v143, v143 op_sel_hi:[0,0,0]
	v_mfma_scale_f32_16x16x128_f8f6f4 v[100:103], v[162:169], v[190:197], v[100:103], v143, v143 op_sel_hi:[0,0,0]
	v_mfma_scale_f32_16x16x128_f8f6f4 v[96:99], v[174:181], v[190:197], v[96:99], v143, v143 op_sel_hi:[0,0,0]
	v_mfma_scale_f32_16x16x128_f8f6f4 v[182:185], v[162:169], v[198:205], v[84:87], v143, v143 op_sel_hi:[0,0,0]
	v_mfma_scale_f32_16x16x128_f8f6f4 v[186:189], v[174:181], v[198:205], v[80:83], v143, v143 op_sel_hi:[0,0,0]
	v_mfma_scale_f32_16x16x128_f8f6f4 v[190:193], v[162:169], v[206:213], v[68:71], v143, v143 op_sel_hi:[0,0,0]
	v_mfma_scale_f32_16x16x128_f8f6f4 v[194:197], v[174:181], v[206:213], v[64:67], v143, v143 op_sel_hi:[0,0,0]
	s_setprio 0
	s_barrier
	s_and_b32 s25, s22, 0xffff
	s_mov_b32 m0, s79
	s_mov_b32 s26, s18
	s_mov_b32 s27, s19
	s_add_u32 s16, s24, 0x4000
	buffer_load_dwordx4 v137, s[24:27], 0 offen lds
	s_mov_b32 m0, s80
	s_addc_u32 s17, s22, 0
	buffer_load_dwordx4 v139, s[24:27], 0 offen lds
	s_and_b32 s17, s17, 0xffff
	s_mov_b32 m0, s81
	s_and_b32 s29, s23, 0xffff
	buffer_load_dwordx4 v137, s[16:19], 0 offen lds
	s_mov_b32 m0, s82
	s_mov_b32 s30, s18
	buffer_load_dwordx4 v139, s[16:19], 0 offen lds
	s_mov_b32 s31, s19
	s_mov_b32 m0, s76
	s_nop 0
	buffer_load_dwordx4 v136, s[28:31], 0 offen lds
	s_mov_b32 m0, s83
	s_nop 0
	buffer_load_dwordx4 v138, s[28:31], 0 offen lds
	ds_read_b128 v[64:67], v142 offset:16384
	ds_read_b128 v[68:71], v142 offset:17408
	ds_read_b128 v[72:75], v142 offset:18432
	ds_read_b128 v[76:79], v142 offset:19456
	ds_read_b128 v[80:83], v142 offset:20480
	ds_read_b128 v[84:87], v142 offset:21504
	ds_read_b128 v[88:91], v142 offset:22528
	ds_read_b128 v[92:95], v142 offset:23552
	s_waitcnt vmcnt(8)
	s_waitcnt lgkmcnt(0)
	s_barrier
	s_setprio 1
	v_mfma_scale_f32_16x16x128_f8f6f4 v[60:63], v[146:153], v[64:71], v[60:63], v143, v143 op_sel_hi:[0,0,0]
	v_mfma_scale_f32_16x16x128_f8f6f4 v[56:59], v[154:161], v[64:71], v[56:59], v143, v143 op_sel_hi:[0,0,0]
	v_mfma_scale_f32_16x16x128_f8f6f4 v[198:201], v[146:153], v[72:79], v[44:47], v143, v143 op_sel_hi:[0,0,0]
	v_mfma_scale_f32_16x16x128_f8f6f4 v[202:205], v[154:161], v[72:79], v[40:43], v143, v143 op_sel_hi:[0,0,0]
	v_mfma_scale_f32_16x16x128_f8f6f4 v[206:209], v[146:153], v[80:87], v[28:31], v143, v143 op_sel_hi:[0,0,0]
	v_mfma_scale_f32_16x16x128_f8f6f4 v[210:213], v[154:161], v[80:87], v[24:27], v143, v143 op_sel_hi:[0,0,0]
	v_mfma_scale_f32_16x16x128_f8f6f4 v[226:229], v[146:153], v[88:95], v[12:15], v143, v143 op_sel_hi:[0,0,0]
	v_mfma_scale_f32_16x16x128_f8f6f4 v[230:233], v[154:161], v[88:95], v[8:11], v143, v143 op_sel_hi:[0,0,0]
	s_setprio 0
	s_setprio 1
	v_mfma_scale_f32_16x16x128_f8f6f4 v[52:55], v[162:169], v[64:71], v[52:55], v143, v143 op_sel_hi:[0,0,0]
	v_mfma_scale_f32_16x16x128_f8f6f4 v[48:51], v[174:181], v[64:71], v[48:51], v143, v143 op_sel_hi:[0,0,0]
	v_mfma_scale_f32_16x16x128_f8f6f4 v[234:237], v[162:169], v[72:79], v[36:39], v143, v143 op_sel_hi:[0,0,0]
	v_mfma_scale_f32_16x16x128_f8f6f4 v[238:241], v[174:181], v[72:79], v[32:35], v143, v143 op_sel_hi:[0,0,0]
	v_mfma_scale_f32_16x16x128_f8f6f4 v[242:245], v[162:169], v[80:87], v[20:23], v143, v143 op_sel_hi:[0,0,0]
	v_mfma_scale_f32_16x16x128_f8f6f4 v[246:249], v[174:181], v[80:87], v[16:19], v143, v143 op_sel_hi:[0,0,0]
	v_mfma_scale_f32_16x16x128_f8f6f4 v[250:253], v[162:169], v[88:95], v[4:7], v143, v143 op_sel_hi:[0,0,0]
	v_mfma_scale_f32_16x16x128_f8f6f4 v[170:173], v[174:181], v[88:95], v[0:3], v143, v143 op_sel_hi:[0,0,0]
	s_setprio 0
	s_barrier
; #define PG8_STAGE(bufoff, gbase, voff) do { const __amdgpu_buffer_rsrc_t _rs = __builtin_amdgcn_make_buffer_rsrc((void*)(gbase), 0, 0x7fffffff, 0x00020000); _Pragma("unroll") for (int _i = 0; _i < 2; ++_i) \
;         __builtin_amdgcn_raw_ptr_buffer_load_lds(_rs, (LAS unsigned*)(lds + (bufoff) + ldsw + _i * 8192), 16, (int)(voff)[_i], 0, 0, 0); } while (0)
; #define PG8_WAIT_V(n) asm volatile("s_waitcnt vmcnt(" #n ")" ::: "memory")
; #define PG8_WAIT_L(n) asm volatile("s_waitcnt lgkmcnt(" #n ")" ::: "memory")
; #define PG8_BAR __builtin_amdgcn_s_barrier()
; #define PG8_SCHED __builtin_amdgcn_sched_barrier(0)
; template <class Epi, class Sched, bool F8 = false>
; __device__ __forceinline__ void gemm_phase(LAS unsigned char* lds, const int lda, const int ldb, const Sched& S, const Epi& E) {
;     ...
;             PG8_LDB(B0, 1, 0); PG8_LDB(B1, 1, 1); PG8_SCHED; PG8_LDA(At, 1, 0); PG8_STAGE(PG8_SA(0, 1), a2 + hstepA, voffA);
;             PG8_WAIT_V(8); PG8_WAIT_L(0); PG8_BAR; PG8_MMA(0, 0, At, B0); PG8_MMA(0, 1, At, B1); PG8_BAR; PG8_SCHED;
;             PG8_LDA(At, 1, 1); PG8_STAGE(PG8_SB(1, 0), b3, voffB); PG8_STAGE(PG8_SB(1, 1), b3 + hstepB, voffB); PG8_STAGE(PG8_SA(1, 0), a3, voffA);
;             PG8_WAIT_V(8); PG8_WAIT_L(0); PG8_BAR; PG8_MMA(1, 0, At, B0); PG8_MMA(1, 1, At, B1); PG8_BAR; PG8_SCHED;
	s_nop 4
	s_add_u32 s16, s28, 0x80000
	s_addc_u32 s17, s23, 0
	s_and_b32 s17, s17, 0xffff
	s_mov_b32 m0, s84
	s_nop 0
	buffer_load_dwordx4 v136, s[16:19], 0 offen lds
	s_mov_b32 m0, s85
	s_nop 0
	buffer_load_dwordx4 v138, s[16:19], 0 offen lds
	ds_read_b128 v[0:3], v144
	ds_read_b128 v[4:7], v144 offset:1024
	ds_read_b128 v[16:19], v144 offset:2048
	ds_read_b128 v[20:23], v144 offset:3072
	ds_read_b128 v[146:149], v145
	ds_read_b128 v[150:153], v145 offset:1024
	ds_read_b128 v[154:157], v145 offset:2048
	ds_read_b128 v[158:161], v145 offset:3072
	ds_read_b128 v[8:11], v142 offset:32768
	ds_read_b128 v[12:15], v142 offset:33792
	ds_read_b128 v[24:27], v142 offset:34816
	ds_read_b128 v[28:31], v142 offset:35840
	ds_read_b128 v[32:35], v142 offset:36864
	ds_read_b128 v[36:39], v142 offset:37888
	ds_read_b128 v[40:43], v142 offset:38912
	ds_read_b128 v[44:47], v142 offset:39936
	s_waitcnt vmcnt(8)
	s_waitcnt lgkmcnt(0)
	s_barrier
	s_setprio 1
	v_mfma_scale_f32_16x16x128_f8f6f4 v[124:127], v[0:7], v[8:15], v[124:127], v143, v143 op_sel_hi:[0,0,0]
	v_mfma_scale_f32_16x16x128_f8f6f4 v[120:123], v[16:23], v[8:15], v[120:123], v143, v143 op_sel_hi:[0,0,0]
	v_mfma_scale_f32_16x16x128_f8f6f4 v[108:111], v[0:7], v[24:31], v[108:111], v143, v143 op_sel_hi:[0,0,0]
	v_mfma_scale_f32_16x16x128_f8f6f4 v[104:107], v[16:23], v[24:31], v[104:107], v143, v143 op_sel_hi:[0,0,0]
	v_mfma_scale_f32_16x16x128_f8f6f4 v[92:95], v[0:7], v[32:39], v[132:135], v143, v143 op_sel_hi:[0,0,0]
	v_mfma_scale_f32_16x16x128_f8f6f4 v[88:91], v[16:23], v[32:39], v[214:217], v143, v143 op_sel_hi:[0,0,0]
	v_mfma_scale_f32_16x16x128_f8f6f4 v[76:79], v[0:7], v[40:47], v[218:221], v143, v143 op_sel_hi:[0,0,0]
	v_mfma_scale_f32_16x16x128_f8f6f4 v[72:75], v[16:23], v[40:47], v[222:225], v143, v143 op_sel_hi:[0,0,0]
	s_setprio 0
	s_setprio 1
	v_mfma_scale_f32_16x16x128_f8f6f4 v[116:119], v[146:153], v[8:15], v[116:119], v143, v143 op_sel_hi:[0,0,0]
	v_mfma_scale_f32_16x16x128_f8f6f4 v[112:115], v[154:161], v[8:15], v[112:115], v143, v143 op_sel_hi:[0,0,0]
	v_mfma_scale_f32_16x16x128_f8f6f4 v[100:103], v[146:153], v[24:31], v[100:103], v143, v143 op_sel_hi:[0,0,0]
	v_mfma_scale_f32_16x16x128_f8f6f4 v[96:99], v[154:161], v[24:31], v[96:99], v143, v143 op_sel_hi:[0,0,0]
	v_mfma_scale_f32_16x16x128_f8f6f4 v[84:87], v[146:153], v[32:39], v[182:185], v143, v143 op_sel_hi:[0,0,0]
	v_mfma_scale_f32_16x16x128_f8f6f4 v[80:83], v[154:161], v[32:39], v[186:189], v143, v143 op_sel_hi:[0,0,0]
	v_mfma_scale_f32_16x16x128_f8f6f4 v[68:71], v[146:153], v[40:47], v[190:193], v143, v143 op_sel_hi:[0,0,0]
	v_mfma_scale_f32_16x16x128_f8f6f4 v[64:67], v[154:161], v[40:47], v[194:197], v143, v143 op_sel_hi:[0,0,0]
	s_setprio 0
	s_barrier
	s_add_u32 s16, s24, 0x8000
	s_addc_u32 s17, s22, 0
	s_mov_b32 m0, s90
	s_and_b32 s17, s17, 0xffff
	buffer_load_dwordx4 v137, s[16:19], 0 offen lds
	s_mov_b32 m0, s91
	s_mov_b32 s23, s19
	buffer_load_dwordx4 v139, s[16:19], 0 offen lds
	s_add_u32 s16, s24, 0xc000
	s_addc_u32 s17, s22, 0
	s_and_b32 s17, s17, 0xffff
	s_mov_b32 m0, s94
	s_and_b32 s21, s21, 0xffff
	buffer_load_dwordx4 v137, s[16:19], 0 offen lds
	s_mov_b32 m0, s95
	s_mov_b32 s22, s18
	buffer_load_dwordx4 v139, s[16:19], 0 offen lds
	s_mov_b32 m0, s92
	s_nop 0
	buffer_load_dwordx4 v136, s[20:23], 0 offen lds
	s_mov_b32 m0, s93
	s_nop 0
	buffer_load_dwordx4 v138, s[20:23], 0 offen lds
	ds_read_b128 v[32:35], v142 offset:49152
	ds_read_b128 v[36:39], v142 offset:50176
	ds_read_b128 v[162:165], v142 offset:51200
	ds_read_b128 v[166:169], v142 offset:52224
	ds_read_b128 v[174:177], v142 offset:53248
	ds_read_b128 v[178:181], v142 offset:54272
	ds_read_b128 v[182:185], v142 offset:55296
	ds_read_b128 v[186:189], v142 offset:56320
	s_waitcnt vmcnt(8)
	s_waitcnt lgkmcnt(0)
	s_barrier
	s_setprio 1
	v_mfma_scale_f32_16x16x128_f8f6f4 v[60:63], v[0:7], v[32:39], v[60:63], v143, v143 op_sel_hi:[0,0,0]
	v_mfma_scale_f32_16x16x128_f8f6f4 v[56:59], v[16:23], v[32:39], v[56:59], v143, v143 op_sel_hi:[0,0,0]
	v_mfma_scale_f32_16x16x128_f8f6f4 v[44:47], v[0:7], v[162:169], v[198:201], v143, v143 op_sel_hi:[0,0,0]
	v_mfma_scale_f32_16x16x128_f8f6f4 v[40:43], v[16:23], v[162:169], v[202:205], v143, v143 op_sel_hi:[0,0,0]
	v_mfma_scale_f32_16x16x128_f8f6f4 v[28:31], v[0:7], v[174:181], v[206:209], v143, v143 op_sel_hi:[0,0,0]
	v_mfma_scale_f32_16x16x128_f8f6f4 v[24:27], v[16:23], v[174:181], v[210:213], v143, v143 op_sel_hi:[0,0,0]
	v_mfma_scale_f32_16x16x128_f8f6f4 v[12:15], v[0:7], v[182:189], v[226:229], v143, v143 op_sel_hi:[0,0,0]
	v_mfma_scale_f32_16x16x128_f8f6f4 v[8:11], v[16:23], v[182:189], v[230:233], v143, v143 op_sel_hi:[0,0,0]
	s_setprio 0
	s_setprio 1
	v_mfma_scale_f32_16x16x128_f8f6f4 v[52:55], v[146:153], v[32:39], v[52:55], v143, v143 op_sel_hi:[0,0,0]
	v_mfma_scale_f32_16x16x128_f8f6f4 v[48:51], v[154:161], v[32:39], v[48:51], v143, v143 op_sel_hi:[0,0,0]
	v_mfma_scale_f32_16x16x128_f8f6f4 v[36:39], v[146:153], v[162:169], v[234:237], v143, v143 op_sel_hi:[0,0,0]
	v_mfma_scale_f32_16x16x128_f8f6f4 v[32:35], v[154:161], v[162:169], v[238:241], v143, v143 op_sel_hi:[0,0,0]
	v_mfma_scale_f32_16x16x128_f8f6f4 v[20:23], v[146:153], v[174:181], v[242:245], v143, v143 op_sel_hi:[0,0,0]
	v_mfma_scale_f32_16x16x128_f8f6f4 v[16:19], v[154:161], v[174:181], v[246:249], v143, v143 op_sel_hi:[0,0,0]
	v_mfma_scale_f32_16x16x128_f8f6f4 v[4:7], v[146:153], v[182:189], v[250:253], v143, v143 op_sel_hi:[0,0,0]
	v_mfma_scale_f32_16x16x128_f8f6f4 v[0:3], v[154:161], v[182:189], v[170:173], v143, v143 op_sel_hi:[0,0,0]
	s_setprio 0
	s_barrier
	s_add_i32 s69, s69, 2
	s_add_u32 s7, s7, 0x10000
	s_addc_u32 s62, s62, 0
	s_add_u32 s63, s63, 0x100
	s_addc_u32 s67, s67, 0
	s_cmp_gt_u32 s69, 29
	s_cbranch_scc0 .LBB0_174
	s_and_b64 vcc, exec, s[38:39]
	s_cbranch_vccz .LBB0_177
	s_barrier

; #define PG8_STAGE(bufoff, gbase, voff) do { const __amdgpu_buffer_rsrc_t _rs = __builtin_amdgcn_make_buffer_rsrc((void*)(gbase), 0, 0x7fffffff, 0x00020000); _Pragma("unroll") for (int _i = 0; _i < 2; ++_i) \
;         __builtin_amdgcn_raw_ptr_buffer_load_lds(_rs, (LAS unsigned*)(lds + (bufoff) + ldsw + _i * 8192), 16, (int)(voff)[_i], 0, 0, 0); } while (0)
; #define PG8_WAIT_V(n) asm volatile("s_waitcnt vmcnt(" #n ")" ::: "memory")
; #define PG8_WAIT_L(n) asm volatile("s_waitcnt lgkmcnt(" #n ")" ::: "memory")
; #define PG8_BAR __builtin_amdgcn_s_barrier()
; #define PG8_SCHED __builtin_amdgcn_sched_barrier(0)
; template <class Epi, class Sched, bool F8 = false>
; __device__ __forceinline__ void gemm_phase(LAS unsigned char* lds, const int lda, const int ldb, const Sched& S, const Epi& E) {
;     ...
;             const char* a1 = cA + (size_t)(t + 1) * kstep;
;             const char* a2 = last ? nA : cA + (size_t)(t + 2) * kstep; const char* b2 = last ? nB : cB + (size_t)(t + 2) * kstepB;
;             const char* a3 = a2 + kstep; const char* b3 = b2 + kstepB;
;     ...
;             PG8_LDB(B0, 0, 0); PG8_LDB(B1, 0, 1); PG8_SCHED; PG8_LDA(At, 0, 0); PG8_STAGE(PG8_SA(1, 1), a1 + hstepA, voffA);
;             PG8_WAIT_V(8); PG8_WAIT_L(0); PG8_BAR; PG8_MMA(0, 0, At, B0); PG8_MMA(0, 1, At, B1); PG8_BAR; PG8_SCHED;
;             PG8_LDA(At, 0, 1); PG8_STAGE(PG8_SB(0, 0), b2, voffB); PG8_STAGE(PG8_SB(0, 1), b2 + hstepB, voffB); PG8_STAGE(PG8_SA(0, 0), a2, voffA);
;             PG8_WAIT_V(8); PG8_WAIT_L(0); PG8_BAR; PG8_MMA(1, 0, At, B0); PG8_MMA(1, 1, At, B1); PG8_BAR; PG8_SCHED;
.LBB0_408:
	s_add_i32 s64, s4, 2
	s_add_u32 s5, vcc_hi, 0xfff80080
	s_addc_u32 s16, s35, -1
	s_cmp_eq_u32 s62, s4
	s_cselect_b32 s40, s70, s5
	s_cselect_b32 s19, s71, s16
	s_cselect_b32 s18, s73, vcc_lo
	s_cselect_b32 s36, s72, s63
	s_add_u32 s16, s40, 0x80
	s_addc_u32 s17, s19, 0
	s_and_b32 s5, s35, 0xffff
	s_mov_b32 s4, vcc_hi
	s_mov_b32 m0, s92
	s_nop 0
	buffer_load_dwordx4 v176, s[4:7], 0 offen lds
	s_mov_b32 m0, s93
	s_nop 0
	buffer_load_dwordx4 v178, s[4:7], 0 offen lds
	ds_read_b128 v[104:107], v180
	ds_read_b128 v[108:111], v180 offset:1024
	ds_read_b128 v[136:139], v180 offset:2048
	ds_read_b128 v[140:143], v180 offset:3072
	ds_read_b128 v[148:151], v181
	ds_read_b128 v[152:155], v181 offset:1024
	ds_read_b128 v[156:159], v181 offset:2048
	ds_read_b128 v[160:163], v181 offset:3072
	ds_read_b128 v[164:167], v182
	ds_read_b128 v[168:171], v182 offset:1024
	ds_read_b128 v[172:175], v182 offset:2048
	ds_read_b128 v[186:189], v182 offset:3072
	ds_read_b128 v[190:193], v182 offset:4096
	ds_read_b128 v[194:197], v182 offset:5120
	ds_read_b128 v[198:201], v182 offset:6144
	ds_read_b128 v[202:205], v182 offset:7168
	s_waitcnt vmcnt(8)
	s_waitcnt lgkmcnt(0)
	s_barrier
	s_setprio 1
	v_mfma_f32_16x16x32_bf16 v[132:135], v[104:107], v[164:167], v[132:135]
	v_mfma_f32_16x16x32_bf16 v[128:131], v[136:139], v[164:167], v[128:131]
	v_mfma_f32_16x16x32_bf16 v[124:127], v[104:107], v[172:175], v[124:127]
	v_mfma_f32_16x16x32_bf16 v[120:123], v[136:139], v[172:175], v[120:123]
	v_mfma_f32_16x16x32_bf16 v[116:119], v[104:107], v[190:193], v[116:119]
	v_mfma_f32_16x16x32_bf16 v[112:115], v[136:139], v[190:193], v[112:115]
	v_mfma_f32_16x16x32_bf16 v[100:103], v[104:107], v[198:201], v[100:103]
	v_mfma_f32_16x16x32_bf16 v[96:99], v[136:139], v[198:201], v[96:99]
	v_mfma_f32_16x16x32_bf16 v[132:135], v[108:111], v[168:171], v[132:135]
	v_mfma_f32_16x16x32_bf16 v[128:131], v[140:143], v[168:171], v[128:131]
	v_mfma_f32_16x16x32_bf16 v[124:127], v[108:111], v[186:189], v[124:127]
	v_mfma_f32_16x16x32_bf16 v[120:123], v[140:143], v[186:189], v[120:123]
	v_mfma_f32_16x16x32_bf16 v[116:119], v[108:111], v[194:197], v[116:119]
	v_mfma_f32_16x16x32_bf16 v[112:115], v[140:143], v[194:197], v[112:115]
	v_mfma_f32_16x16x32_bf16 v[100:103], v[108:111], v[202:205], v[100:103]
	v_mfma_f32_16x16x32_bf16 v[96:99], v[140:143], v[202:205], v[96:99]
	s_setprio 0
	s_setprio 1
	v_mfma_f32_16x16x32_bf16 v[60:63], v[148:151], v[164:167], v[60:63]
	v_mfma_f32_16x16x32_bf16 v[56:59], v[156:159], v[164:167], v[56:59]
	v_mfma_f32_16x16x32_bf16 v[52:55], v[148:151], v[172:175], v[52:55]
	v_mfma_f32_16x16x32_bf16 v[48:51], v[156:159], v[172:175], v[48:51]
	v_mfma_f32_16x16x32_bf16 v[44:47], v[148:151], v[190:193], v[44:47]
	v_mfma_f32_16x16x32_bf16 v[40:43], v[156:159], v[190:193], v[40:43]
	v_mfma_f32_16x16x32_bf16 v[36:39], v[148:151], v[198:201], v[36:39]
	v_mfma_f32_16x16x32_bf16 v[32:35], v[156:159], v[198:201], v[32:35]
	v_mfma_f32_16x16x32_bf16 v[60:63], v[152:155], v[168:171], v[60:63]
	v_mfma_f32_16x16x32_bf16 v[56:59], v[160:163], v[168:171], v[56:59]
	v_mfma_f32_16x16x32_bf16 v[52:55], v[152:155], v[186:189], v[52:55]
	v_mfma_f32_16x16x32_bf16 v[48:51], v[160:163], v[186:189], v[48:51]
	v_mfma_f32_16x16x32_bf16 v[44:47], v[152:155], v[194:197], v[44:47]
	v_mfma_f32_16x16x32_bf16 v[40:43], v[160:163], v[194:197], v[40:43]
	v_mfma_f32_16x16x32_bf16 v[36:39], v[152:155], v[202:205], v[36:39]
	v_mfma_f32_16x16x32_bf16 v[32:35], v[160:163], v[202:205], v[32:35]
	s_setprio 0
	s_barrier
	s_and_b32 s37, s18, 0xffff
	s_mov_b32 m0, s75
	s_mov_b32 s38, s6
	s_mov_b32 s39, s7
	s_add_u32 s4, s36, 0x4000
	buffer_load_dwordx4 v177, s[36:39], 0 offen lds
	s_mov_b32 m0, s77
	s_addc_u32 s5, s18, 0
	buffer_load_dwordx4 v179, s[36:39], 0 offen lds
	s_and_b32 s5, s5, 0xffff
	s_mov_b32 m0, s78
	s_and_b32 s41, s19, 0xffff
	buffer_load_dwordx4 v177, s[4:7], 0 offen lds
	s_mov_b32 m0, s79
	s_mov_b32 s42, s6
	buffer_load_dwordx4 v179, s[4:7], 0 offen lds
	s_mov_b32 s43, s7
	s_mov_b32 m0, s74
	s_nop 0
	buffer_load_dwordx4 v176, s[40:43], 0 offen lds
	s_mov_b32 m0, s80
	s_nop 0
	buffer_load_dwordx4 v178, s[40:43], 0 offen lds
	ds_read_b128 v[164:167], v182 offset:16384
	ds_read_b128 v[168:171], v182 offset:17408
	ds_read_b128 v[172:175], v182 offset:18432
	ds_read_b128 v[186:189], v182 offset:19456
	ds_read_b128 v[190:193], v182 offset:20480
	ds_read_b128 v[194:197], v182 offset:21504
	ds_read_b128 v[198:201], v182 offset:22528
	ds_read_b128 v[202:205], v182 offset:23552
	s_waitcnt vmcnt(8)
	s_waitcnt lgkmcnt(0)
	s_barrier
; #define PG8_STAGE(bufoff, gbase, voff) do { const __amdgpu_buffer_rsrc_t _rs = __builtin_amdgcn_make_buffer_rsrc((void*)(gbase), 0, 0x7fffffff, 0x00020000); _Pragma("unroll") for (int _i = 0; _i < 2; ++_i) \
;         __builtin_amdgcn_raw_ptr_buffer_load_lds(_rs, (LAS unsigned*)(lds + (bufoff) + ldsw + _i * 8192), 16, (int)(voff)[_i], 0, 0, 0); } while (0)
; #define PG8_WAIT_V(n) asm volatile("s_waitcnt vmcnt(" #n ")" ::: "memory")
; #define PG8_WAIT_L(n) asm volatile("s_waitcnt lgkmcnt(" #n ")" ::: "memory")
; #define PG8_BAR __builtin_amdgcn_s_barrier()
; #define PG8_SCHED __builtin_amdgcn_sched_barrier(0)
; template <class Epi, class Sched, bool F8 = false>
; __device__ __forceinline__ void gemm_phase(LAS unsigned char* lds, const int lda, const int ldb, const Sched& S, const Epi& E) {
;     ...
;             PG8_WAIT_V(8); PG8_WAIT_L(0); PG8_BAR; PG8_MMA(1, 0, At, B0); PG8_MMA(1, 1, At, B1); PG8_BAR; PG8_SCHED;
;             PG8_LDB(B0, 1, 0); PG8_LDB(B1, 1, 1); PG8_SCHED; PG8_LDA(At, 1, 0); PG8_STAGE(PG8_SA(0, 1), a2 + hstepA, voffA);
;             PG8_WAIT_V(8); PG8_WAIT_L(0); PG8_BAR; PG8_MMA(0, 0, At, B0); PG8_MMA(0, 1, At, B1); PG8_BAR; PG8_SCHED;
	s_setprio 1
	v_mfma_f32_16x16x32_bf16 v[92:95], v[104:107], v[164:167], v[92:95]
	v_mfma_f32_16x16x32_bf16 v[88:91], v[136:139], v[164:167], v[88:91]
	v_mfma_f32_16x16x32_bf16 v[84:87], v[104:107], v[172:175], v[84:87]
	v_mfma_f32_16x16x32_bf16 v[80:83], v[136:139], v[172:175], v[80:83]
	v_mfma_f32_16x16x32_bf16 v[76:79], v[104:107], v[190:193], v[76:79]
	v_mfma_f32_16x16x32_bf16 v[72:75], v[136:139], v[190:193], v[72:75]
	v_mfma_f32_16x16x32_bf16 v[68:71], v[104:107], v[198:201], v[68:71]
	v_mfma_f32_16x16x32_bf16 v[64:67], v[136:139], v[198:201], v[64:67]
	v_mfma_f32_16x16x32_bf16 v[92:95], v[108:111], v[168:171], v[92:95]
	v_mfma_f32_16x16x32_bf16 v[88:91], v[140:143], v[168:171], v[88:91]
	v_mfma_f32_16x16x32_bf16 v[84:87], v[108:111], v[186:189], v[84:87]
	v_mfma_f32_16x16x32_bf16 v[80:83], v[140:143], v[186:189], v[80:83]
	v_mfma_f32_16x16x32_bf16 v[76:79], v[108:111], v[194:197], v[76:79]
	v_mfma_f32_16x16x32_bf16 v[72:75], v[140:143], v[194:197], v[72:75]
	v_mfma_f32_16x16x32_bf16 v[68:71], v[108:111], v[202:205], v[68:71]
	v_mfma_f32_16x16x32_bf16 v[64:67], v[140:143], v[202:205], v[64:67]
	s_setprio 0
	s_setprio 1
	v_mfma_f32_16x16x32_bf16 v[28:31], v[148:151], v[164:167], v[28:31]
	v_mfma_f32_16x16x32_bf16 v[24:27], v[156:159], v[164:167], v[24:27]
	v_mfma_f32_16x16x32_bf16 v[20:23], v[148:151], v[172:175], v[20:23]
	v_mfma_f32_16x16x32_bf16 v[16:19], v[156:159], v[172:175], v[16:19]
	v_mfma_f32_16x16x32_bf16 v[12:15], v[148:151], v[190:193], v[12:15]
	v_mfma_f32_16x16x32_bf16 v[8:11], v[156:159], v[190:193], v[8:11]
	v_mfma_f32_16x16x32_bf16 v[4:7], v[148:151], v[198:201], v[4:7]
	v_mfma_f32_16x16x32_bf16 v[0:3], v[156:159], v[198:201], v[0:3]
	v_mfma_f32_16x16x32_bf16 v[28:31], v[152:155], v[168:171], v[28:31]
	v_mfma_f32_16x16x32_bf16 v[24:27], v[160:163], v[168:171], v[24:27]
	v_mfma_f32_16x16x32_bf16 v[20:23], v[152:155], v[186:189], v[20:23]
	v_mfma_f32_16x16x32_bf16 v[16:19], v[160:163], v[186:189], v[16:19]
	v_mfma_f32_16x16x32_bf16 v[12:15], v[152:155], v[194:197], v[12:15]
	v_mfma_f32_16x16x32_bf16 v[8:11], v[160:163], v[194:197], v[8:11]
	v_mfma_f32_16x16x32_bf16 v[4:7], v[152:155], v[202:205], v[4:7]
	v_mfma_f32_16x16x32_bf16 v[0:3], v[160:163], v[202:205], v[0:3]
	s_setprio 0
	s_barrier
	s_add_u32 s4, s40, 0x80000
	s_addc_u32 s5, s19, 0
	s_and_b32 s5, s5, 0xffff
	s_mov_b32 m0, s81
	s_nop 0
	buffer_load_dwordx4 v176, s[4:7], 0 offen lds
	s_mov_b32 m0, s82
	s_nop 0
	buffer_load_dwordx4 v178, s[4:7], 0 offen lds
	ds_read_b128 v[104:107], v183
	ds_read_b128 v[108:111], v183 offset:1024
	ds_read_b128 v[136:139], v183 offset:2048
	ds_read_b128 v[140:143], v183 offset:3072
	ds_read_b128 v[148:151], v184
	ds_read_b128 v[152:155], v184 offset:1024
	ds_read_b128 v[156:159], v184 offset:2048
	ds_read_b128 v[160:163], v184 offset:3072
	ds_read_b128 v[164:167], v182 offset:32768
	ds_read_b128 v[168:171], v182 offset:33792
	ds_read_b128 v[172:175], v182 offset:34816
	ds_read_b128 v[186:189], v182 offset:35840
	ds_read_b128 v[190:193], v182 offset:36864
	ds_read_b128 v[194:197], v182 offset:37888
	ds_read_b128 v[198:201], v182 offset:38912
	ds_read_b128 v[202:205], v182 offset:39936
	s_waitcnt vmcnt(8)
	s_waitcnt lgkmcnt(0)
	s_barrier
	s_setprio 1
	v_mfma_f32_16x16x32_bf16 v[132:135], v[104:107], v[164:167], v[132:135]
	v_mfma_f32_16x16x32_bf16 v[128:131], v[136:139], v[164:167], v[128:131]
	v_mfma_f32_16x16x32_bf16 v[124:127], v[104:107], v[172:175], v[124:127]
	v_mfma_f32_16x16x32_bf16 v[120:123], v[136:139], v[172:175], v[120:123]
	v_mfma_f32_16x16x32_bf16 v[116:119], v[104:107], v[190:193], v[116:119]
	v_mfma_f32_16x16x32_bf16 v[112:115], v[136:139], v[190:193], v[112:115]
	v_mfma_f32_16x16x32_bf16 v[100:103], v[104:107], v[198:201], v[100:103]
	v_mfma_f32_16x16x32_bf16 v[96:99], v[136:139], v[198:201], v[96:99]
	v_mfma_f32_16x16x32_bf16 v[132:135], v[108:111], v[168:171], v[132:135]
	v_mfma_f32_16x16x32_bf16 v[128:131], v[140:143], v[168:171], v[128:131]
	v_mfma_f32_16x16x32_bf16 v[124:127], v[108:111], v[186:189], v[124:127]
	v_mfma_f32_16x16x32_bf16 v[120:123], v[140:143], v[186:189], v[120:123]
	v_mfma_f32_16x16x32_bf16 v[116:119], v[108:111], v[194:197], v[116:119]
	v_mfma_f32_16x16x32_bf16 v[112:115], v[140:143], v[194:197], v[112:115]
	v_mfma_f32_16x16x32_bf16 v[100:103], v[108:111], v[202:205], v[100:103]
	v_mfma_f32_16x16x32_bf16 v[96:99], v[140:143], v[202:205], v[96:99]
	s_setprio 0
	s_setprio 1
	v_mfma_f32_16x16x32_bf16 v[60:63], v[148:151], v[164:167], v[60:63]
	v_mfma_f32_16x16x32_bf16 v[56:59], v[156:159], v[164:167], v[56:59]
	v_mfma_f32_16x16x32_bf16 v[52:55], v[148:151], v[172:175], v[52:55]
	v_mfma_f32_16x16x32_bf16 v[48:51], v[156:159], v[172:175], v[48:51]
	v_mfma_f32_16x16x32_bf16 v[44:47], v[148:151], v[190:193], v[44:47]
	v_mfma_f32_16x16x32_bf16 v[40:43], v[156:159], v[190:193], v[40:43]
	v_mfma_f32_16x16x32_bf16 v[36:39], v[148:151], v[198:201], v[36:39]
	v_mfma_f32_16x16x32_bf16 v[32:35], v[156:159], v[198:201], v[32:35]
	v_mfma_f32_16x16x32_bf16 v[60:63], v[152:155], v[168:171], v[60:63]
	v_mfma_f32_16x16x32_bf16 v[56:59], v[160:163], v[168:171], v[56:59]
	v_mfma_f32_16x16x32_bf16 v[52:55], v[152:155], v[186:189], v[52:55]
	v_mfma_f32_16x16x32_bf16 v[48:51], v[160:163], v[186:189], v[48:51]
	v_mfma_f32_16x16x32_bf16 v[44:47], v[152:155], v[194:197], v[44:47]
	v_mfma_f32_16x16x32_bf16 v[40:43], v[160:163], v[194:197], v[40:43]
	v_mfma_f32_16x16x32_bf16 v[36:39], v[152:155], v[202:205], v[36:39]
	v_mfma_f32_16x16x32_bf16 v[32:35], v[160:163], v[202:205], v[32:35]
	s_setprio 0
	s_barrier
; #define PG8_STAGE(bufoff, gbase, voff) do { const __amdgpu_buffer_rsrc_t _rs = __builtin_amdgcn_make_buffer_rsrc((void*)(gbase), 0, 0x7fffffff, 0x00020000); _Pragma("unroll") for (int _i = 0; _i < 2; ++_i) \
;         __builtin_amdgcn_raw_ptr_buffer_load_lds(_rs, (LAS unsigned*)(lds + (bufoff) + ldsw + _i * 8192), 16, (int)(voff)[_i], 0, 0, 0); } while (0)
; #define PG8_WAIT_V(n) asm volatile("s_waitcnt vmcnt(" #n ")" ::: "memory")
; #define PG8_WAIT_L(n) asm volatile("s_waitcnt lgkmcnt(" #n ")" ::: "memory")
; #define PG8_BAR __builtin_amdgcn_s_barrier()
; #define PG8_SCHED __builtin_amdgcn_sched_barrier(0)
; template <class Epi, class Sched, bool F8 = false>
; __device__ __forceinline__ void gemm_phase(LAS unsigned char* lds, const int lda, const int ldb, const Sched& S, const Epi& E) {
;     ...
;             PG8_LDA(At, 1, 1); PG8_STAGE(PG8_SB(1, 0), b3, voffB); PG8_STAGE(PG8_SB(1, 1), b3 + hstepB, voffB); PG8_STAGE(PG8_SA(1, 0), a3, voffA);
;             PG8_WAIT_V(8); PG8_WAIT_L(0); PG8_BAR; PG8_MMA(1, 0, At, B0); PG8_MMA(1, 1, At, B1); PG8_BAR; PG8_SCHED;
	s_add_u32 s4, s36, 0x8000
	s_addc_u32 s5, s18, 0
	s_mov_b32 m0, s86
	s_and_b32 s5, s5, 0xffff
	buffer_load_dwordx4 v177, s[4:7], 0 offen lds
	s_mov_b32 m0, s87
	s_mov_b32 s19, s7
	buffer_load_dwordx4 v179, s[4:7], 0 offen lds
	s_add_u32 s4, s36, 0xc000
	s_addc_u32 s5, s18, 0
	s_and_b32 s5, s5, 0xffff
	s_mov_b32 m0, s90
	s_and_b32 s17, s17, 0xffff
	buffer_load_dwordx4 v177, s[4:7], 0 offen lds
	s_mov_b32 m0, s91
	s_mov_b32 s18, s6
	buffer_load_dwordx4 v179, s[4:7], 0 offen lds
	s_mov_b32 m0, s88
	s_nop 0
	buffer_load_dwordx4 v176, s[16:19], 0 offen lds
	s_mov_b32 m0, s89
	s_nop 0
	buffer_load_dwordx4 v178, s[16:19], 0 offen lds
	ds_read_b128 v[164:167], v182 offset:49152
	ds_read_b128 v[168:171], v182 offset:50176
	ds_read_b128 v[172:175], v182 offset:51200
	ds_read_b128 v[186:189], v182 offset:52224
	ds_read_b128 v[190:193], v182 offset:53248
	ds_read_b128 v[194:197], v182 offset:54272
	ds_read_b128 v[198:201], v182 offset:55296
	ds_read_b128 v[202:205], v182 offset:56320
	s_waitcnt vmcnt(8)
	s_waitcnt lgkmcnt(0)
	s_barrier
	s_setprio 1
	v_mfma_f32_16x16x32_bf16 v[92:95], v[104:107], v[164:167], v[92:95]
	v_mfma_f32_16x16x32_bf16 v[88:91], v[136:139], v[164:167], v[88:91]
	v_mfma_f32_16x16x32_bf16 v[84:87], v[104:107], v[172:175], v[84:87]
	v_mfma_f32_16x16x32_bf16 v[80:83], v[136:139], v[172:175], v[80:83]
	v_mfma_f32_16x16x32_bf16 v[76:79], v[104:107], v[190:193], v[76:79]
	v_mfma_f32_16x16x32_bf16 v[72:75], v[136:139], v[190:193], v[72:75]
	v_mfma_f32_16x16x32_bf16 v[68:71], v[104:107], v[198:201], v[68:71]
	v_mfma_f32_16x16x32_bf16 v[64:67], v[136:139], v[198:201], v[64:67]
	v_mfma_f32_16x16x32_bf16 v[92:95], v[108:111], v[168:171], v[92:95]
	v_mfma_f32_16x16x32_bf16 v[88:91], v[140:143], v[168:171], v[88:91]
	v_mfma_f32_16x16x32_bf16 v[84:87], v[108:111], v[186:189], v[84:87]
	v_mfma_f32_16x16x32_bf16 v[80:83], v[140:143], v[186:189], v[80:83]
	v_mfma_f32_16x16x32_bf16 v[76:79], v[108:111], v[194:197], v[76:79]
	v_mfma_f32_16x16x32_bf16 v[72:75], v[140:143], v[194:197], v[72:75]
	v_mfma_f32_16x16x32_bf16 v[68:71], v[108:111], v[202:205], v[68:71]
	v_mfma_f32_16x16x32_bf16 v[64:67], v[140:143], v[202:205], v[64:67]
	s_setprio 0
	s_setprio 1
	v_mfma_f32_16x16x32_bf16 v[28:31], v[148:151], v[164:167], v[28:31]
	v_mfma_f32_16x16x32_bf16 v[24:27], v[156:159], v[164:167], v[24:27]
	v_mfma_f32_16x16x32_bf16 v[20:23], v[148:151], v[172:175], v[20:23]
	v_mfma_f32_16x16x32_bf16 v[16:19], v[156:159], v[172:175], v[16:19]
	v_mfma_f32_16x16x32_bf16 v[12:15], v[148:151], v[190:193], v[12:15]
	v_mfma_f32_16x16x32_bf16 v[8:11], v[156:159], v[190:193], v[8:11]
	v_mfma_f32_16x16x32_bf16 v[4:7], v[148:151], v[198:201], v[4:7]
	v_mfma_f32_16x16x32_bf16 v[0:3], v[156:159], v[198:201], v[0:3]
	v_mfma_f32_16x16x32_bf16 v[28:31], v[152:155], v[168:171], v[28:31]
	v_mfma_f32_16x16x32_bf16 v[24:27], v[160:163], v[168:171], v[24:27]
	v_mfma_f32_16x16x32_bf16 v[20:23], v[152:155], v[186:189], v[20:23]
	v_mfma_f32_16x16x32_bf16 v[16:19], v[160:163], v[186:189], v[16:19]
	v_mfma_f32_16x16x32_bf16 v[12:15], v[152:155], v[194:197], v[12:15]
	v_mfma_f32_16x16x32_bf16 v[8:11], v[160:163], v[194:197], v[8:11]
	v_mfma_f32_16x16x32_bf16 v[4:7], v[152:155], v[202:205], v[4:7]
	v_mfma_f32_16x16x32_bf16 v[0:3], v[160:163], v[202:205], v[0:3]
	s_setprio 0
	s_barrier
	s_add_u32 s63, s63, 0x10000
	s_addc_u32 vcc_lo, vcc_lo, 0
	s_add_u32 vcc_hi, vcc_hi, 0x100
	s_addc_u32 s35, s35, 0
	s_cmp_ge_i32 s64, s9
	s_mov_b32 s4, s64
	s_cbranch_scc0 .LBB0_408
	s_and_b64 vcc, exec, s[66:67]
	s_cbranch_vccz .LBB0_411
	s_barrier

; #define PG8_STAGE(bufoff, gbase, voff) do { const __amdgpu_buffer_rsrc_t _rs = __builtin_amdgcn_make_buffer_rsrc((void*)(gbase), 0, 0x7fffffff, 0x00020000); _Pragma("unroll") for (int _i = 0; _i < 2; ++_i) \
;         __builtin_amdgcn_raw_ptr_buffer_load_lds(_rs, (LAS unsigned*)(lds + (bufoff) + ldsw + _i * 8192), 16, (int)(voff)[_i], 0, 0, 0); } while (0)
; #define PG8_WAIT_V(n) asm volatile("s_waitcnt vmcnt(" #n ")" ::: "memory")
; #define PG8_WAIT_L(n) asm volatile("s_waitcnt lgkmcnt(" #n ")" ::: "memory")
; #define PG8_BAR __builtin_amdgcn_s_barrier()
; #define PG8_SCHED __builtin_amdgcn_sched_barrier(0)
; template <class Epi, class Sched, bool F8 = false>
; __device__ __forceinline__ void gemm_phase(LAS unsigned char* lds, const int lda, const int ldb, const Sched& S, const Epi& E) {
;     ...
;             const char* a1 = cA + (size_t)(t + 1) * kstep;
;             const char* a2 = last ? nA : cA + (size_t)(t + 2) * kstep; const char* b2 = last ? nB : cB + (size_t)(t + 2) * kstepB;
;             const char* a3 = a2 + kstep; const char* b3 = b2 + kstepB;
;     ...
;             PG8_LDB(B0, 0, 0); PG8_LDB(B1, 0, 1); PG8_SCHED; PG8_LDA(At, 0, 0); PG8_STAGE(PG8_SA(1, 1), a1 + hstepA, voffA);
;             PG8_WAIT_V(8); PG8_WAIT_L(0); PG8_BAR; PG8_MMA(0, 0, At, B0); PG8_MMA(0, 1, At, B1); PG8_BAR; PG8_SCHED;
;             PG8_LDA(At, 0, 1); PG8_STAGE(PG8_SB(0, 0), b2, voffB); PG8_STAGE(PG8_SB(0, 1), b2 + hstepB, voffB); PG8_STAGE(PG8_SA(0, 0), a2, voffA);
;             PG8_WAIT_V(8); PG8_WAIT_L(0); PG8_BAR; PG8_MMA(1, 0, At, B0); PG8_MMA(1, 1, At, B1); PG8_BAR; PG8_SCHED;
.LBB0_485:
	s_add_u32 s4, s47, 0xfff80080
	s_addc_u32 s5, s62, -1
	s_cmp_eq_u32 s63, 28
	s_cselect_b32 s40, s48, s4
	s_cselect_b32 s19, s49, s5
	s_cselect_b32 s18, s51, s33
	s_cselect_b32 s36, s50, s9
	s_add_u32 s16, s40, 0x80
	s_addc_u32 s17, s19, 0
	s_and_b32 s5, s62, 0xffff
	s_mov_b32 s4, s47
	s_mov_b32 m0, s91
	s_nop 0
	buffer_load_dwordx4 v148, s[4:7], 0 offen lds
	s_mov_b32 m0, s92
	s_nop 0
	buffer_load_dwordx4 v150, s[4:7], 0 offen lds
	v_add_u32_e32 v144, 0x10000, v152
	v_add_u32_e32 v166, 0x14000, v152
	ds_read_b128 v[132:135], v144
	ds_read_b128 v[136:139], v144 offset:1024
	ds_read_b128 v[140:143], v144 offset:2048
	ds_read_b128 v[144:147], v144 offset:3072
	ds_read_b128 v[154:157], v166
	ds_read_b128 v[158:161], v166 offset:1024
	ds_read_b128 v[162:165], v166 offset:2048
	ds_read_b128 v[166:169], v166 offset:3072
	ds_read_b128 v[170:173], v153
	ds_read_b128 v[174:177], v153 offset:1024
	ds_read_b128 v[178:181], v153 offset:2048
	ds_read_b128 v[182:185], v153 offset:3072
	ds_read_b128 v[186:189], v153 offset:4096
	ds_read_b128 v[190:193], v153 offset:5120
	ds_read_b128 v[194:197], v153 offset:6144
	ds_read_b128 v[198:201], v153 offset:7168
	s_waitcnt vmcnt(8)
	s_waitcnt lgkmcnt(0)
	s_barrier
	s_setprio 1
	v_mfma_f32_16x16x32_bf16 v[124:127], v[132:135], v[170:173], v[124:127]
	v_mfma_f32_16x16x32_bf16 v[120:123], v[140:143], v[170:173], v[120:123]
	v_mfma_f32_16x16x32_bf16 v[116:119], v[132:135], v[178:181], v[116:119]
	v_mfma_f32_16x16x32_bf16 v[112:115], v[140:143], v[178:181], v[112:115]
	v_mfma_f32_16x16x32_bf16 v[108:111], v[132:135], v[186:189], v[108:111]
	v_mfma_f32_16x16x32_bf16 v[104:107], v[140:143], v[186:189], v[104:107]
	v_mfma_f32_16x16x32_bf16 v[100:103], v[132:135], v[194:197], v[100:103]
	v_mfma_f32_16x16x32_bf16 v[96:99], v[140:143], v[194:197], v[96:99]
	v_mfma_f32_16x16x32_bf16 v[124:127], v[136:139], v[174:177], v[124:127]
	v_mfma_f32_16x16x32_bf16 v[120:123], v[144:147], v[174:177], v[120:123]
	v_mfma_f32_16x16x32_bf16 v[116:119], v[136:139], v[182:185], v[116:119]
	v_mfma_f32_16x16x32_bf16 v[112:115], v[144:147], v[182:185], v[112:115]
	v_mfma_f32_16x16x32_bf16 v[108:111], v[136:139], v[190:193], v[108:111]
	v_mfma_f32_16x16x32_bf16 v[104:107], v[144:147], v[190:193], v[104:107]
	v_mfma_f32_16x16x32_bf16 v[100:103], v[136:139], v[198:201], v[100:103]
	v_mfma_f32_16x16x32_bf16 v[96:99], v[144:147], v[198:201], v[96:99]
	s_setprio 0
	s_setprio 1
	v_mfma_f32_16x16x32_bf16 v[92:95], v[154:157], v[170:173], v[92:95]
	v_mfma_f32_16x16x32_bf16 v[88:91], v[162:165], v[170:173], v[88:91]
	v_mfma_f32_16x16x32_bf16 v[84:87], v[154:157], v[178:181], v[84:87]
	v_mfma_f32_16x16x32_bf16 v[80:83], v[162:165], v[178:181], v[80:83]
	v_mfma_f32_16x16x32_bf16 v[76:79], v[154:157], v[186:189], v[76:79]
	v_mfma_f32_16x16x32_bf16 v[72:75], v[162:165], v[186:189], v[72:75]
	v_mfma_f32_16x16x32_bf16 v[68:71], v[154:157], v[194:197], v[68:71]
	v_mfma_f32_16x16x32_bf16 v[64:67], v[162:165], v[194:197], v[64:67]
	v_mfma_f32_16x16x32_bf16 v[92:95], v[158:161], v[174:177], v[92:95]
	v_mfma_f32_16x16x32_bf16 v[88:91], v[166:169], v[174:177], v[88:91]
	v_mfma_f32_16x16x32_bf16 v[84:87], v[158:161], v[182:185], v[84:87]
	v_mfma_f32_16x16x32_bf16 v[80:83], v[166:169], v[182:185], v[80:83]
	v_mfma_f32_16x16x32_bf16 v[76:79], v[158:161], v[190:193], v[76:79]
	v_mfma_f32_16x16x32_bf16 v[72:75], v[166:169], v[190:193], v[72:75]
	v_mfma_f32_16x16x32_bf16 v[68:71], v[158:161], v[198:201], v[68:71]
	v_mfma_f32_16x16x32_bf16 v[64:67], v[166:169], v[198:201], v[64:67]
	s_setprio 0
	s_barrier
	s_and_b32 s37, s18, 0xffff
	s_mov_b32 m0, s70
	s_mov_b32 s38, s6
	s_mov_b32 s39, s7
	s_add_u32 s4, s36, 0x4000
	buffer_load_dwordx4 v149, s[36:39], 0 offen lds
	s_mov_b32 m0, s71
	s_addc_u32 s5, s18, 0
	buffer_load_dwordx4 v151, s[36:39], 0 offen lds
	s_and_b32 s5, s5, 0xffff
	s_mov_b32 m0, s72
	s_and_b32 s41, s19, 0xffff
	buffer_load_dwordx4 v149, s[4:7], 0 offen lds
	s_mov_b32 m0, s73
	s_mov_b32 s42, s6
	buffer_load_dwordx4 v151, s[4:7], 0 offen lds
	s_mov_b32 s43, s7
	s_mov_b32 m0, s67
	s_nop 0
	buffer_load_dwordx4 v148, s[40:43], 0 offen lds
	s_mov_b32 m0, s74
	s_nop 0
	buffer_load_dwordx4 v150, s[40:43], 0 offen lds
	ds_read_b128 v[170:173], v153 offset:16384
	ds_read_b128 v[174:177], v153 offset:17408
	ds_read_b128 v[178:181], v153 offset:18432
	ds_read_b128 v[182:185], v153 offset:19456
	ds_read_b128 v[186:189], v153 offset:20480
	ds_read_b128 v[190:193], v153 offset:21504
	ds_read_b128 v[194:197], v153 offset:22528
	ds_read_b128 v[198:201], v153 offset:23552
	s_waitcnt vmcnt(8)
	s_waitcnt lgkmcnt(0)
	s_barrier
; #define PG8_STAGE(bufoff, gbase, voff) do { const __amdgpu_buffer_rsrc_t _rs = __builtin_amdgcn_make_buffer_rsrc((void*)(gbase), 0, 0x7fffffff, 0x00020000); _Pragma("unroll") for (int _i = 0; _i < 2; ++_i) \
;         __builtin_amdgcn_raw_ptr_buffer_load_lds(_rs, (LAS unsigned*)(lds + (bufoff) + ldsw + _i * 8192), 16, (int)(voff)[_i], 0, 0, 0); } while (0)
; #define PG8_WAIT_V(n) asm volatile("s_waitcnt vmcnt(" #n ")" ::: "memory")
; #define PG8_WAIT_L(n) asm volatile("s_waitcnt lgkmcnt(" #n ")" ::: "memory")
; #define PG8_BAR __builtin_amdgcn_s_barrier()
; #define PG8_SCHED __builtin_amdgcn_sched_barrier(0)
; template <class Epi, class Sched, bool F8 = false>
; __device__ __forceinline__ void gemm_phase(LAS unsigned char* lds, const int lda, const int ldb, const Sched& S, const Epi& E) {
;     ...
;             PG8_WAIT_V(8); PG8_WAIT_L(0); PG8_BAR; PG8_MMA(1, 0, At, B0); PG8_MMA(1, 1, At, B1); PG8_BAR; PG8_SCHED;
;             PG8_LDB(B0, 1, 0); PG8_LDB(B1, 1, 1); PG8_SCHED; PG8_LDA(At, 1, 0); PG8_STAGE(PG8_SA(0, 1), a2 + hstepA, voffA);
;             PG8_WAIT_V(8); PG8_WAIT_L(0); PG8_BAR; PG8_MMA(0, 0, At, B0); PG8_MMA(0, 1, At, B1); PG8_BAR; PG8_SCHED;
	s_setprio 1
	v_mfma_f32_16x16x32_bf16 v[60:63], v[132:135], v[170:173], v[60:63]
	v_mfma_f32_16x16x32_bf16 v[56:59], v[140:143], v[170:173], v[56:59]
	v_mfma_f32_16x16x32_bf16 v[52:55], v[132:135], v[178:181], v[52:55]
	v_mfma_f32_16x16x32_bf16 v[48:51], v[140:143], v[178:181], v[48:51]
	v_mfma_f32_16x16x32_bf16 v[44:47], v[132:135], v[186:189], v[44:47]
	v_mfma_f32_16x16x32_bf16 v[40:43], v[140:143], v[186:189], v[40:43]
	v_mfma_f32_16x16x32_bf16 v[36:39], v[132:135], v[194:197], v[36:39]
	v_mfma_f32_16x16x32_bf16 v[32:35], v[140:143], v[194:197], v[32:35]
	v_mfma_f32_16x16x32_bf16 v[60:63], v[136:139], v[174:177], v[60:63]
	v_mfma_f32_16x16x32_bf16 v[56:59], v[144:147], v[174:177], v[56:59]
	v_mfma_f32_16x16x32_bf16 v[52:55], v[136:139], v[182:185], v[52:55]
	v_mfma_f32_16x16x32_bf16 v[48:51], v[144:147], v[182:185], v[48:51]
	v_mfma_f32_16x16x32_bf16 v[44:47], v[136:139], v[190:193], v[44:47]
	v_mfma_f32_16x16x32_bf16 v[40:43], v[144:147], v[190:193], v[40:43]
	v_mfma_f32_16x16x32_bf16 v[36:39], v[136:139], v[198:201], v[36:39]
	v_mfma_f32_16x16x32_bf16 v[32:35], v[144:147], v[198:201], v[32:35]
	s_setprio 0
	s_setprio 1
	v_mfma_f32_16x16x32_bf16 v[28:31], v[154:157], v[170:173], v[28:31]
	v_mfma_f32_16x16x32_bf16 v[24:27], v[162:165], v[170:173], v[24:27]
	v_mfma_f32_16x16x32_bf16 v[20:23], v[154:157], v[178:181], v[20:23]
	v_mfma_f32_16x16x32_bf16 v[16:19], v[162:165], v[178:181], v[16:19]
	v_mfma_f32_16x16x32_bf16 v[12:15], v[154:157], v[186:189], v[12:15]
	v_mfma_f32_16x16x32_bf16 v[8:11], v[162:165], v[186:189], v[8:11]
	v_mfma_f32_16x16x32_bf16 v[4:7], v[154:157], v[194:197], v[4:7]
	v_mfma_f32_16x16x32_bf16 v[0:3], v[162:165], v[194:197], v[0:3]
	v_mfma_f32_16x16x32_bf16 v[28:31], v[158:161], v[174:177], v[28:31]
	v_mfma_f32_16x16x32_bf16 v[24:27], v[166:169], v[174:177], v[24:27]
	v_mfma_f32_16x16x32_bf16 v[20:23], v[158:161], v[182:185], v[20:23]
	v_mfma_f32_16x16x32_bf16 v[16:19], v[166:169], v[182:185], v[16:19]
	v_mfma_f32_16x16x32_bf16 v[12:15], v[158:161], v[190:193], v[12:15]
	v_mfma_f32_16x16x32_bf16 v[8:11], v[166:169], v[190:193], v[8:11]
	v_mfma_f32_16x16x32_bf16 v[4:7], v[158:161], v[198:201], v[4:7]
	v_mfma_f32_16x16x32_bf16 v[0:3], v[166:169], v[198:201], v[0:3]
	s_setprio 0
	s_barrier
	s_add_u32 s4, s40, 0x80000
	s_addc_u32 s5, s19, 0
	s_and_b32 s5, s5, 0xffff
	s_mov_b32 m0, s75
	s_nop 0
	buffer_load_dwordx4 v148, s[4:7], 0 offen lds
	s_mov_b32 m0, s76
	s_nop 0
	buffer_load_dwordx4 v150, s[4:7], 0 offen lds
	v_add_u32_e32 v144, 0x18000, v152
	v_add_u32_e32 v166, 0x1c000, v152
	ds_read_b128 v[132:135], v144
	ds_read_b128 v[136:139], v144 offset:1024
	ds_read_b128 v[140:143], v144 offset:2048
	ds_read_b128 v[144:147], v144 offset:3072
	ds_read_b128 v[154:157], v166
	ds_read_b128 v[158:161], v166 offset:1024
	ds_read_b128 v[162:165], v166 offset:2048
	ds_read_b128 v[166:169], v166 offset:3072
	ds_read_b128 v[170:173], v153 offset:32768
	ds_read_b128 v[174:177], v153 offset:33792
	ds_read_b128 v[178:181], v153 offset:34816
	ds_read_b128 v[182:185], v153 offset:35840
	ds_read_b128 v[186:189], v153 offset:36864
	ds_read_b128 v[190:193], v153 offset:37888
	ds_read_b128 v[194:197], v153 offset:38912
	ds_read_b128 v[198:201], v153 offset:39936
	s_waitcnt vmcnt(8)
	s_waitcnt lgkmcnt(0)
	s_barrier
	s_setprio 1
	v_mfma_f32_16x16x32_bf16 v[124:127], v[132:135], v[170:173], v[124:127]
	v_mfma_f32_16x16x32_bf16 v[120:123], v[140:143], v[170:173], v[120:123]
	v_mfma_f32_16x16x32_bf16 v[116:119], v[132:135], v[178:181], v[116:119]
	v_mfma_f32_16x16x32_bf16 v[112:115], v[140:143], v[178:181], v[112:115]
	v_mfma_f32_16x16x32_bf16 v[108:111], v[132:135], v[186:189], v[108:111]
	v_mfma_f32_16x16x32_bf16 v[104:107], v[140:143], v[186:189], v[104:107]
	v_mfma_f32_16x16x32_bf16 v[100:103], v[132:135], v[194:197], v[100:103]
	v_mfma_f32_16x16x32_bf16 v[96:99], v[140:143], v[194:197], v[96:99]
	v_mfma_f32_16x16x32_bf16 v[124:127], v[136:139], v[174:177], v[124:127]
	v_mfma_f32_16x16x32_bf16 v[120:123], v[144:147], v[174:177], v[120:123]
	v_mfma_f32_16x16x32_bf16 v[116:119], v[136:139], v[182:185], v[116:119]
	v_mfma_f32_16x16x32_bf16 v[112:115], v[144:147], v[182:185], v[112:115]
	v_mfma_f32_16x16x32_bf16 v[108:111], v[136:139], v[190:193], v[108:111]
	v_mfma_f32_16x16x32_bf16 v[104:107], v[144:147], v[190:193], v[104:107]
	v_mfma_f32_16x16x32_bf16 v[100:103], v[136:139], v[198:201], v[100:103]
	v_mfma_f32_16x16x32_bf16 v[96:99], v[144:147], v[198:201], v[96:99]
	s_setprio 0
	s_setprio 1
	v_mfma_f32_16x16x32_bf16 v[92:95], v[154:157], v[170:173], v[92:95]
	v_mfma_f32_16x16x32_bf16 v[88:91], v[162:165], v[170:173], v[88:91]
	v_mfma_f32_16x16x32_bf16 v[84:87], v[154:157], v[178:181], v[84:87]
	v_mfma_f32_16x16x32_bf16 v[80:83], v[162:165], v[178:181], v[80:83]
	v_mfma_f32_16x16x32_bf16 v[76:79], v[154:157], v[186:189], v[76:79]
	v_mfma_f32_16x16x32_bf16 v[72:75], v[162:165], v[186:189], v[72:75]
	v_mfma_f32_16x16x32_bf16 v[68:71], v[154:157], v[194:197], v[68:71]
	v_mfma_f32_16x16x32_bf16 v[64:67], v[162:165], v[194:197], v[64:67]
	v_mfma_f32_16x16x32_bf16 v[92:95], v[158:161], v[174:177], v[92:95]
	v_mfma_f32_16x16x32_bf16 v[88:91], v[166:169], v[174:177], v[88:91]
	v_mfma_f32_16x16x32_bf16 v[84:87], v[158:161], v[182:185], v[84:87]
	v_mfma_f32_16x16x32_bf16 v[80:83], v[166:169], v[182:185], v[80:83]
	v_mfma_f32_16x16x32_bf16 v[76:79], v[158:161], v[190:193], v[76:79]
	v_mfma_f32_16x16x32_bf16 v[72:75], v[166:169], v[190:193], v[72:75]
	v_mfma_f32_16x16x32_bf16 v[68:71], v[158:161], v[198:201], v[68:71]
	v_mfma_f32_16x16x32_bf16 v[64:67], v[166:169], v[198:201], v[64:67]
	s_setprio 0
	s_barrier
; #define PG8_STAGE(bufoff, gbase, voff) do { const __amdgpu_buffer_rsrc_t _rs = __builtin_amdgcn_make_buffer_rsrc((void*)(gbase), 0, 0x7fffffff, 0x00020000); _Pragma("unroll") for (int _i = 0; _i < 2; ++_i) \
;         __builtin_amdgcn_raw_ptr_buffer_load_lds(_rs, (LAS unsigned*)(lds + (bufoff) + ldsw + _i * 8192), 16, (int)(voff)[_i], 0, 0, 0); } while (0)
; #define PG8_WAIT_V(n) asm volatile("s_waitcnt vmcnt(" #n ")" ::: "memory")
; #define PG8_WAIT_L(n) asm volatile("s_waitcnt lgkmcnt(" #n ")" ::: "memory")
; #define PG8_BAR __builtin_amdgcn_s_barrier()
; #define PG8_SCHED __builtin_amdgcn_sched_barrier(0)
; template <class Epi, class Sched, bool F8 = false>
; __device__ __forceinline__ void gemm_phase(LAS unsigned char* lds, const int lda, const int ldb, const Sched& S, const Epi& E) {
;     ...
;             PG8_LDA(At, 1, 1); PG8_STAGE(PG8_SB(1, 0), b3, voffB); PG8_STAGE(PG8_SB(1, 1), b3 + hstepB, voffB); PG8_STAGE(PG8_SA(1, 0), a3, voffA);
;             PG8_WAIT_V(8); PG8_WAIT_L(0); PG8_BAR; PG8_MMA(1, 0, At, B0); PG8_MMA(1, 1, At, B1); PG8_BAR; PG8_SCHED;
	s_add_u32 s4, s36, 0x8000
	s_addc_u32 s5, s18, 0
	s_mov_b32 m0, s85
	s_and_b32 s5, s5, 0xffff
	buffer_load_dwordx4 v149, s[4:7], 0 offen lds
	s_mov_b32 m0, s86
	s_mov_b32 s19, s7
	buffer_load_dwordx4 v151, s[4:7], 0 offen lds
	s_add_u32 s4, s36, 0xc000
	s_addc_u32 s5, s18, 0
	s_and_b32 s5, s5, 0xffff
	s_mov_b32 m0, s89
	s_and_b32 s17, s17, 0xffff
	buffer_load_dwordx4 v149, s[4:7], 0 offen lds
	s_mov_b32 m0, s90
	s_mov_b32 s18, s6
	buffer_load_dwordx4 v151, s[4:7], 0 offen lds
	s_mov_b32 m0, s87
	s_nop 0
	buffer_load_dwordx4 v148, s[16:19], 0 offen lds
	s_mov_b32 m0, s88
	s_nop 0
	buffer_load_dwordx4 v150, s[16:19], 0 offen lds
	ds_read_b128 v[170:173], v153 offset:49152
	ds_read_b128 v[174:177], v153 offset:50176
	ds_read_b128 v[178:181], v153 offset:51200
	ds_read_b128 v[182:185], v153 offset:52224
	ds_read_b128 v[186:189], v153 offset:53248
	ds_read_b128 v[190:193], v153 offset:54272
	ds_read_b128 v[194:197], v153 offset:55296
	ds_read_b128 v[198:201], v153 offset:56320
	s_waitcnt vmcnt(8)
	s_waitcnt lgkmcnt(0)
	s_barrier
	s_setprio 1
	v_mfma_f32_16x16x32_bf16 v[60:63], v[132:135], v[170:173], v[60:63]
	v_mfma_f32_16x16x32_bf16 v[56:59], v[140:143], v[170:173], v[56:59]
	v_mfma_f32_16x16x32_bf16 v[52:55], v[132:135], v[178:181], v[52:55]
	v_mfma_f32_16x16x32_bf16 v[48:51], v[140:143], v[178:181], v[48:51]
	v_mfma_f32_16x16x32_bf16 v[44:47], v[132:135], v[186:189], v[44:47]
	v_mfma_f32_16x16x32_bf16 v[40:43], v[140:143], v[186:189], v[40:43]
	v_mfma_f32_16x16x32_bf16 v[36:39], v[132:135], v[194:197], v[36:39]
	v_mfma_f32_16x16x32_bf16 v[32:35], v[140:143], v[194:197], v[32:35]
	v_mfma_f32_16x16x32_bf16 v[60:63], v[136:139], v[174:177], v[60:63]
	v_mfma_f32_16x16x32_bf16 v[56:59], v[144:147], v[174:177], v[56:59]
	v_mfma_f32_16x16x32_bf16 v[52:55], v[136:139], v[182:185], v[52:55]
	v_mfma_f32_16x16x32_bf16 v[48:51], v[144:147], v[182:185], v[48:51]
	v_mfma_f32_16x16x32_bf16 v[44:47], v[136:139], v[190:193], v[44:47]
	v_mfma_f32_16x16x32_bf16 v[40:43], v[144:147], v[190:193], v[40:43]
	v_mfma_f32_16x16x32_bf16 v[36:39], v[136:139], v[198:201], v[36:39]
	v_mfma_f32_16x16x32_bf16 v[32:35], v[144:147], v[198:201], v[32:35]
	s_setprio 0
	s_setprio 1
	v_mfma_f32_16x16x32_bf16 v[28:31], v[154:157], v[170:173], v[28:31]
	v_mfma_f32_16x16x32_bf16 v[24:27], v[162:165], v[170:173], v[24:27]
	v_mfma_f32_16x16x32_bf16 v[20:23], v[154:157], v[178:181], v[20:23]
	v_mfma_f32_16x16x32_bf16 v[16:19], v[162:165], v[178:181], v[16:19]
	v_mfma_f32_16x16x32_bf16 v[12:15], v[154:157], v[186:189], v[12:15]
	v_mfma_f32_16x16x32_bf16 v[8:11], v[162:165], v[186:189], v[8:11]
	v_mfma_f32_16x16x32_bf16 v[4:7], v[154:157], v[194:197], v[4:7]
	v_mfma_f32_16x16x32_bf16 v[0:3], v[162:165], v[194:197], v[0:3]
	v_mfma_f32_16x16x32_bf16 v[28:31], v[158:161], v[174:177], v[28:31]
	v_mfma_f32_16x16x32_bf16 v[24:27], v[166:169], v[174:177], v[24:27]
	v_mfma_f32_16x16x32_bf16 v[20:23], v[158:161], v[182:185], v[20:23]
	v_mfma_f32_16x16x32_bf16 v[16:19], v[166:169], v[182:185], v[16:19]
	v_mfma_f32_16x16x32_bf16 v[12:15], v[158:161], v[190:193], v[12:15]
	v_mfma_f32_16x16x32_bf16 v[8:11], v[166:169], v[190:193], v[8:11]
	v_mfma_f32_16x16x32_bf16 v[4:7], v[158:161], v[198:201], v[4:7]
	v_mfma_f32_16x16x32_bf16 v[0:3], v[166:169], v[198:201], v[0:3]
	s_setprio 0
	s_barrier
	s_add_i32 s63, s63, 2
	s_add_u32 s9, s9, 0x10000
	s_addc_u32 s33, s33, 0
	s_add_u32 s47, s47, 0x100
	s_addc_u32 s62, s62, 0
	s_cmp_gt_u32 s63, 29
	s_cbranch_scc0 .LBB0_485
	s_and_b64 vcc, exec, s[44:45]
	s_cbranch_vccz .LBB0_488
	s_barrier

; #define PG8_STAGE(bufoff, gbase, voff) do { const __amdgpu_buffer_rsrc_t _rs = __builtin_amdgcn_make_buffer_rsrc((void*)(gbase), 0, 0x7fffffff, 0x00020000); _Pragma("unroll") for (int _i = 0; _i < 2; ++_i) \
;         __builtin_amdgcn_raw_ptr_buffer_load_lds(_rs, (LAS unsigned*)(lds + (bufoff) + ldsw + _i * 8192), 16, (int)(voff)[_i], 0, 0, 0); } while (0)
; #define PG8_WAIT_V(n) asm volatile("s_waitcnt vmcnt(" #n ")" ::: "memory")
; #define PG8_WAIT_L(n) asm volatile("s_waitcnt lgkmcnt(" #n ")" ::: "memory")
; #define PG8_BAR __builtin_amdgcn_s_barrier()
; #define PG8_SCHED __builtin_amdgcn_sched_barrier(0)
; template <class Epi, class Sched, bool F8 = false>
; __device__ __forceinline__ void gemm_phase(LAS unsigned char* lds, const int lda, const int ldb, const Sched& S, const Epi& E) {
;     ...
;             const char* a1 = cA + (size_t)(t + 1) * kstep;
;             const char* a2 = last ? nA : cA + (size_t)(t + 2) * kstep; const char* b2 = last ? nB : cB + (size_t)(t + 2) * kstepB;
;             const char* a3 = a2 + kstep; const char* b3 = b2 + kstepB;
;     ...
;             PG8_LDB(B0, 0, 0); PG8_LDB(B1, 0, 1); PG8_SCHED; PG8_LDA(At, 0, 0); PG8_STAGE(PG8_SA(1, 1), a1 + hstepA, voffA);
;             PG8_WAIT_V(8); PG8_WAIT_L(0); PG8_BAR; PG8_MMA(0, 0, At, B0); PG8_MMA(0, 1, At, B1); PG8_BAR; PG8_SCHED;
;             PG8_LDA(At, 0, 1); PG8_STAGE(PG8_SB(0, 0), b2, voffB); PG8_STAGE(PG8_SB(0, 1), b2 + hstepB, voffB); PG8_STAGE(PG8_SA(0, 0), a2, voffA);
;             PG8_WAIT_V(8); PG8_WAIT_L(0); PG8_BAR; PG8_MMA(1, 0, At, B0); PG8_MMA(1, 1, At, B1); PG8_BAR; PG8_SCHED;
.LBB0_632:
	s_add_u32 s4, vcc_lo, 0xfff00080
	s_addc_u32 s5, vcc_hi, -1
	s_cmp_eq_u32 s64, 60
	s_cselect_b32 s40, s68, s4
	s_cselect_b32 s19, s69, s5
	s_cselect_b32 s18, s71, s67
	s_cselect_b32 s36, s70, s51
	s_add_u32 s16, s40, 0x80
	s_addc_u32 s17, s19, 0
	s_and_b32 s5, vcc_hi, 0xffff
	s_mov_b32 s4, vcc_lo
	s_mov_b32 m0, s92
	s_nop 0
	buffer_load_dwordx4 v138, s[4:7], 0 offen lds
	s_mov_b32 m0, s93
	s_nop 0
	buffer_load_dwordx4 v140, s[4:7], 0 offen lds
	ds_read_b128 v[132:135], v142
	ds_read_b128 v[148:151], v142 offset:1024
	ds_read_b128 v[152:155], v142 offset:2048
	ds_read_b128 v[156:159], v142 offset:3072
	ds_read_b128 v[160:163], v143
	ds_read_b128 v[164:167], v143 offset:1024
	ds_read_b128 v[168:171], v143 offset:2048
	ds_read_b128 v[172:175], v143 offset:3072
	ds_read_b128 v[176:179], v144
	ds_read_b128 v[180:183], v144 offset:1024
	ds_read_b128 v[184:187], v144 offset:2048
	ds_read_b128 v[188:191], v144 offset:3072
	ds_read_b128 v[192:195], v144 offset:4096
	ds_read_b128 v[196:199], v144 offset:5120
	ds_read_b128 v[200:203], v144 offset:6144
	ds_read_b128 v[204:207], v144 offset:7168
	s_waitcnt vmcnt(8)
	s_waitcnt lgkmcnt(0)
	s_barrier
	s_setprio 1
	v_mfma_f32_16x16x32_bf16 v[124:127], v[132:135], v[176:179], v[124:127]
	v_mfma_f32_16x16x32_bf16 v[120:123], v[152:155], v[176:179], v[120:123]
	v_mfma_f32_16x16x32_bf16 v[108:111], v[132:135], v[184:187], v[108:111]
	v_mfma_f32_16x16x32_bf16 v[104:107], v[152:155], v[184:187], v[104:107]
	v_mfma_f32_16x16x32_bf16 v[92:95], v[132:135], v[192:195], v[92:95]
	v_mfma_f32_16x16x32_bf16 v[88:91], v[152:155], v[192:195], v[88:91]
	v_mfma_f32_16x16x32_bf16 v[76:79], v[132:135], v[200:203], v[76:79]
	v_mfma_f32_16x16x32_bf16 v[72:75], v[152:155], v[200:203], v[72:75]
	v_mfma_f32_16x16x32_bf16 v[124:127], v[148:151], v[180:183], v[124:127]
	v_mfma_f32_16x16x32_bf16 v[120:123], v[156:159], v[180:183], v[120:123]
	v_mfma_f32_16x16x32_bf16 v[108:111], v[148:151], v[188:191], v[108:111]
	v_mfma_f32_16x16x32_bf16 v[104:107], v[156:159], v[188:191], v[104:107]
	v_mfma_f32_16x16x32_bf16 v[92:95], v[148:151], v[196:199], v[92:95]
	v_mfma_f32_16x16x32_bf16 v[88:91], v[156:159], v[196:199], v[88:91]
	v_mfma_f32_16x16x32_bf16 v[76:79], v[148:151], v[204:207], v[76:79]
	v_mfma_f32_16x16x32_bf16 v[72:75], v[156:159], v[204:207], v[72:75]
	s_setprio 0
	s_setprio 1
	v_mfma_f32_16x16x32_bf16 v[116:119], v[160:163], v[176:179], v[116:119]
	v_mfma_f32_16x16x32_bf16 v[112:115], v[168:171], v[176:179], v[112:115]
	v_mfma_f32_16x16x32_bf16 v[100:103], v[160:163], v[184:187], v[100:103]
	v_mfma_f32_16x16x32_bf16 v[96:99], v[168:171], v[184:187], v[96:99]
	v_mfma_f32_16x16x32_bf16 v[84:87], v[160:163], v[192:195], v[84:87]
	v_mfma_f32_16x16x32_bf16 v[80:83], v[168:171], v[192:195], v[80:83]
	v_mfma_f32_16x16x32_bf16 v[68:71], v[160:163], v[200:203], v[68:71]
	v_mfma_f32_16x16x32_bf16 v[64:67], v[168:171], v[200:203], v[64:67]
	v_mfma_f32_16x16x32_bf16 v[116:119], v[164:167], v[180:183], v[116:119]
	v_mfma_f32_16x16x32_bf16 v[112:115], v[172:175], v[180:183], v[112:115]
	v_mfma_f32_16x16x32_bf16 v[100:103], v[164:167], v[188:191], v[100:103]
	v_mfma_f32_16x16x32_bf16 v[96:99], v[172:175], v[188:191], v[96:99]
	v_mfma_f32_16x16x32_bf16 v[84:87], v[164:167], v[196:199], v[84:87]
	v_mfma_f32_16x16x32_bf16 v[80:83], v[172:175], v[196:199], v[80:83]
	v_mfma_f32_16x16x32_bf16 v[68:71], v[164:167], v[204:207], v[68:71]
	v_mfma_f32_16x16x32_bf16 v[64:67], v[172:175], v[204:207], v[64:67]
	s_setprio 0
	s_barrier
	s_and_b32 s37, s18, 0xffff
	s_mov_b32 m0, s73
	s_mov_b32 s38, s6
	s_mov_b32 s39, s7
	s_add_u32 s4, s36, 0x4000
	buffer_load_dwordx4 v139, s[36:39], 0 offen lds
	s_mov_b32 m0, s74
	s_addc_u32 s5, s18, 0
	buffer_load_dwordx4 v141, s[36:39], 0 offen lds
	s_and_b32 s5, s5, 0xffff
	s_mov_b32 m0, s75
	s_and_b32 s41, s19, 0xffff
	buffer_load_dwordx4 v139, s[4:7], 0 offen lds
	s_mov_b32 m0, s76
	s_mov_b32 s42, s6
	buffer_load_dwordx4 v141, s[4:7], 0 offen lds
	s_mov_b32 s43, s7
	s_mov_b32 m0, s61
	s_nop 0
	buffer_load_dwordx4 v138, s[40:43], 0 offen lds
	s_mov_b32 m0, s77
	s_nop 0
	buffer_load_dwordx4 v140, s[40:43], 0 offen lds
	ds_read_b128 v[176:179], v144 offset:16384
	ds_read_b128 v[180:183], v144 offset:17408
	ds_read_b128 v[184:187], v144 offset:18432
	ds_read_b128 v[188:191], v144 offset:19456
	ds_read_b128 v[192:195], v144 offset:20480
	ds_read_b128 v[196:199], v144 offset:21504
	ds_read_b128 v[200:203], v144 offset:22528
	ds_read_b128 v[204:207], v144 offset:23552
	s_waitcnt vmcnt(8)
	s_waitcnt lgkmcnt(0)
	s_barrier
; #define PG8_STAGE(bufoff, gbase, voff) do { const __amdgpu_buffer_rsrc_t _rs = __builtin_amdgcn_make_buffer_rsrc((void*)(gbase), 0, 0x7fffffff, 0x00020000); _Pragma("unroll") for (int _i = 0; _i < 2; ++_i) \
;         __builtin_amdgcn_raw_ptr_buffer_load_lds(_rs, (LAS unsigned*)(lds + (bufoff) + ldsw + _i * 8192), 16, (int)(voff)[_i], 0, 0, 0); } while (0)
; #define PG8_WAIT_V(n) asm volatile("s_waitcnt vmcnt(" #n ")" ::: "memory")
; #define PG8_WAIT_L(n) asm volatile("s_waitcnt lgkmcnt(" #n ")" ::: "memory")
; #define PG8_BAR __builtin_amdgcn_s_barrier()
; #define PG8_SCHED __builtin_amdgcn_sched_barrier(0)
; template <class Epi, class Sched, bool F8 = false>
; __device__ __forceinline__ void gemm_phase(LAS unsigned char* lds, const int lda, const int ldb, const Sched& S, const Epi& E) {
;     ...
;             PG8_WAIT_V(8); PG8_WAIT_L(0); PG8_BAR; PG8_MMA(1, 0, At, B0); PG8_MMA(1, 1, At, B1); PG8_BAR; PG8_SCHED;
;             PG8_LDB(B0, 1, 0); PG8_LDB(B1, 1, 1); PG8_SCHED; PG8_LDA(At, 1, 0); PG8_STAGE(PG8_SA(0, 1), a2 + hstepA, voffA);
;             PG8_WAIT_V(8); PG8_WAIT_L(0); PG8_BAR; PG8_MMA(0, 0, At, B0); PG8_MMA(0, 1, At, B1); PG8_BAR; PG8_SCHED;
	s_setprio 1
	v_mfma_f32_16x16x32_bf16 v[60:63], v[132:135], v[176:179], v[60:63]
	v_mfma_f32_16x16x32_bf16 v[56:59], v[152:155], v[176:179], v[56:59]
	v_mfma_f32_16x16x32_bf16 v[44:47], v[132:135], v[184:187], v[44:47]
	v_mfma_f32_16x16x32_bf16 v[40:43], v[152:155], v[184:187], v[40:43]
	v_mfma_f32_16x16x32_bf16 v[28:31], v[132:135], v[192:195], v[28:31]
	v_mfma_f32_16x16x32_bf16 v[24:27], v[152:155], v[192:195], v[24:27]
	v_mfma_f32_16x16x32_bf16 v[12:15], v[132:135], v[200:203], v[12:15]
	v_mfma_f32_16x16x32_bf16 v[8:11], v[152:155], v[200:203], v[8:11]
	v_mfma_f32_16x16x32_bf16 v[60:63], v[148:151], v[180:183], v[60:63]
	v_mfma_f32_16x16x32_bf16 v[56:59], v[156:159], v[180:183], v[56:59]
	v_mfma_f32_16x16x32_bf16 v[44:47], v[148:151], v[188:191], v[44:47]
	v_mfma_f32_16x16x32_bf16 v[40:43], v[156:159], v[188:191], v[40:43]
	v_mfma_f32_16x16x32_bf16 v[28:31], v[148:151], v[196:199], v[28:31]
	v_mfma_f32_16x16x32_bf16 v[24:27], v[156:159], v[196:199], v[24:27]
	v_mfma_f32_16x16x32_bf16 v[12:15], v[148:151], v[204:207], v[12:15]
	v_mfma_f32_16x16x32_bf16 v[8:11], v[156:159], v[204:207], v[8:11]
	s_setprio 0
	s_setprio 1
	v_mfma_f32_16x16x32_bf16 v[52:55], v[160:163], v[176:179], v[52:55]
	v_mfma_f32_16x16x32_bf16 v[48:51], v[168:171], v[176:179], v[48:51]
	v_mfma_f32_16x16x32_bf16 v[36:39], v[160:163], v[184:187], v[36:39]
	v_mfma_f32_16x16x32_bf16 v[32:35], v[168:171], v[184:187], v[32:35]
	v_mfma_f32_16x16x32_bf16 v[20:23], v[160:163], v[192:195], v[20:23]
	v_mfma_f32_16x16x32_bf16 v[16:19], v[168:171], v[192:195], v[16:19]
	v_mfma_f32_16x16x32_bf16 v[4:7], v[160:163], v[200:203], v[4:7]
	v_mfma_f32_16x16x32_bf16 v[0:3], v[168:171], v[200:203], v[0:3]
	v_mfma_f32_16x16x32_bf16 v[52:55], v[164:167], v[180:183], v[52:55]
	v_mfma_f32_16x16x32_bf16 v[48:51], v[172:175], v[180:183], v[48:51]
	v_mfma_f32_16x16x32_bf16 v[36:39], v[164:167], v[188:191], v[36:39]
	v_mfma_f32_16x16x32_bf16 v[32:35], v[172:175], v[188:191], v[32:35]
	v_mfma_f32_16x16x32_bf16 v[20:23], v[164:167], v[196:199], v[20:23]
	v_mfma_f32_16x16x32_bf16 v[16:19], v[172:175], v[196:199], v[16:19]
	v_mfma_f32_16x16x32_bf16 v[4:7], v[164:167], v[204:207], v[4:7]
	v_mfma_f32_16x16x32_bf16 v[0:3], v[172:175], v[204:207], v[0:3]
	s_setprio 0
	s_barrier
	s_add_u32 s4, s40, 0x100000
	s_addc_u32 s5, s19, 0
	s_and_b32 s5, s5, 0xffff
	s_mov_b32 m0, s78
	s_nop 0
	buffer_load_dwordx4 v138, s[4:7], 0 offen lds
	s_mov_b32 m0, s79
	s_nop 0
	buffer_load_dwordx4 v140, s[4:7], 0 offen lds
	ds_read_b128 v[132:135], v145
	ds_read_b128 v[148:151], v145 offset:1024
	ds_read_b128 v[152:155], v145 offset:2048
	ds_read_b128 v[156:159], v145 offset:3072
	ds_read_b128 v[160:163], v146
	ds_read_b128 v[164:167], v146 offset:1024
	ds_read_b128 v[168:171], v146 offset:2048
	ds_read_b128 v[172:175], v146 offset:3072
	ds_read_b128 v[176:179], v144 offset:32768
	ds_read_b128 v[180:183], v144 offset:33792
	ds_read_b128 v[184:187], v144 offset:34816
	ds_read_b128 v[188:191], v144 offset:35840
	ds_read_b128 v[192:195], v144 offset:36864
	ds_read_b128 v[196:199], v144 offset:37888
	ds_read_b128 v[200:203], v144 offset:38912
	ds_read_b128 v[204:207], v144 offset:39936
	s_waitcnt vmcnt(8)
	s_waitcnt lgkmcnt(0)
	s_barrier
	s_setprio 1
	v_mfma_f32_16x16x32_bf16 v[124:127], v[132:135], v[176:179], v[124:127]
	v_mfma_f32_16x16x32_bf16 v[120:123], v[152:155], v[176:179], v[120:123]
	v_mfma_f32_16x16x32_bf16 v[108:111], v[132:135], v[184:187], v[108:111]
	v_mfma_f32_16x16x32_bf16 v[104:107], v[152:155], v[184:187], v[104:107]
	v_mfma_f32_16x16x32_bf16 v[92:95], v[132:135], v[192:195], v[92:95]
	v_mfma_f32_16x16x32_bf16 v[88:91], v[152:155], v[192:195], v[88:91]
	v_mfma_f32_16x16x32_bf16 v[76:79], v[132:135], v[200:203], v[76:79]
	v_mfma_f32_16x16x32_bf16 v[72:75], v[152:155], v[200:203], v[72:75]
	v_mfma_f32_16x16x32_bf16 v[124:127], v[148:151], v[180:183], v[124:127]
	v_mfma_f32_16x16x32_bf16 v[120:123], v[156:159], v[180:183], v[120:123]
	v_mfma_f32_16x16x32_bf16 v[108:111], v[148:151], v[188:191], v[108:111]
	v_mfma_f32_16x16x32_bf16 v[104:107], v[156:159], v[188:191], v[104:107]
	v_mfma_f32_16x16x32_bf16 v[92:95], v[148:151], v[196:199], v[92:95]
	v_mfma_f32_16x16x32_bf16 v[88:91], v[156:159], v[196:199], v[88:91]
	v_mfma_f32_16x16x32_bf16 v[76:79], v[148:151], v[204:207], v[76:79]
	v_mfma_f32_16x16x32_bf16 v[72:75], v[156:159], v[204:207], v[72:75]
	s_setprio 0
	s_setprio 1
	v_mfma_f32_16x16x32_bf16 v[116:119], v[160:163], v[176:179], v[116:119]
	v_mfma_f32_16x16x32_bf16 v[112:115], v[168:171], v[176:179], v[112:115]
	v_mfma_f32_16x16x32_bf16 v[100:103], v[160:163], v[184:187], v[100:103]
	v_mfma_f32_16x16x32_bf16 v[96:99], v[168:171], v[184:187], v[96:99]
	v_mfma_f32_16x16x32_bf16 v[84:87], v[160:163], v[192:195], v[84:87]
	v_mfma_f32_16x16x32_bf16 v[80:83], v[168:171], v[192:195], v[80:83]
	v_mfma_f32_16x16x32_bf16 v[68:71], v[160:163], v[200:203], v[68:71]
	v_mfma_f32_16x16x32_bf16 v[64:67], v[168:171], v[200:203], v[64:67]
	v_mfma_f32_16x16x32_bf16 v[116:119], v[164:167], v[180:183], v[116:119]
	v_mfma_f32_16x16x32_bf16 v[112:115], v[172:175], v[180:183], v[112:115]
	v_mfma_f32_16x16x32_bf16 v[100:103], v[164:167], v[188:191], v[100:103]
	v_mfma_f32_16x16x32_bf16 v[96:99], v[172:175], v[188:191], v[96:99]
	v_mfma_f32_16x16x32_bf16 v[84:87], v[164:167], v[196:199], v[84:87]
	v_mfma_f32_16x16x32_bf16 v[80:83], v[172:175], v[196:199], v[80:83]
	v_mfma_f32_16x16x32_bf16 v[68:71], v[164:167], v[204:207], v[68:71]
	v_mfma_f32_16x16x32_bf16 v[64:67], v[172:175], v[204:207], v[64:67]
	s_setprio 0
	s_barrier
; #define PG8_STAGE(bufoff, gbase, voff) do { const __amdgpu_buffer_rsrc_t _rs = __builtin_amdgcn_make_buffer_rsrc((void*)(gbase), 0, 0x7fffffff, 0x00020000); _Pragma("unroll") for (int _i = 0; _i < 2; ++_i) \
;         __builtin_amdgcn_raw_ptr_buffer_load_lds(_rs, (LAS unsigned*)(lds + (bufoff) + ldsw + _i * 8192), 16, (int)(voff)[_i], 0, 0, 0); } while (0)
; #define PG8_WAIT_V(n) asm volatile("s_waitcnt vmcnt(" #n ")" ::: "memory")
; #define PG8_WAIT_L(n) asm volatile("s_waitcnt lgkmcnt(" #n ")" ::: "memory")
; #define PG8_BAR __builtin_amdgcn_s_barrier()
; #define PG8_SCHED __builtin_amdgcn_sched_barrier(0)
; template <class Epi, class Sched, bool F8 = false>
; __device__ __forceinline__ void gemm_phase(LAS unsigned char* lds, const int lda, const int ldb, const Sched& S, const Epi& E) {
;     ...
;             PG8_LDA(At, 1, 1); PG8_STAGE(PG8_SB(1, 0), b3, voffB); PG8_STAGE(PG8_SB(1, 1), b3 + hstepB, voffB); PG8_STAGE(PG8_SA(1, 0), a3, voffA);
;             PG8_WAIT_V(8); PG8_WAIT_L(0); PG8_BAR; PG8_MMA(1, 0, At, B0); PG8_MMA(1, 1, At, B1); PG8_BAR; PG8_SCHED;
	s_add_u32 s4, s36, 0x8000
	s_addc_u32 s5, s18, 0
	s_mov_b32 m0, s86
	s_and_b32 s5, s5, 0xffff
	buffer_load_dwordx4 v139, s[4:7], 0 offen lds
	s_mov_b32 m0, s87
	s_mov_b32 s19, s7
	buffer_load_dwordx4 v141, s[4:7], 0 offen lds
	s_add_u32 s4, s36, 0xc000
	s_addc_u32 s5, s18, 0
	s_and_b32 s5, s5, 0xffff
	s_mov_b32 m0, s90
	s_and_b32 s17, s17, 0xffff
	buffer_load_dwordx4 v139, s[4:7], 0 offen lds
	s_mov_b32 m0, s91
	s_mov_b32 s18, s6
	buffer_load_dwordx4 v141, s[4:7], 0 offen lds
	s_mov_b32 m0, s88
	s_nop 0
	buffer_load_dwordx4 v138, s[16:19], 0 offen lds
	s_mov_b32 m0, s89
	s_nop 0
	buffer_load_dwordx4 v140, s[16:19], 0 offen lds
	ds_read_b128 v[176:179], v144 offset:49152
	ds_read_b128 v[180:183], v144 offset:50176
	ds_read_b128 v[184:187], v144 offset:51200
	ds_read_b128 v[188:191], v144 offset:52224
	ds_read_b128 v[192:195], v144 offset:53248
	ds_read_b128 v[196:199], v144 offset:54272
	ds_read_b128 v[200:203], v144 offset:55296
	ds_read_b128 v[204:207], v144 offset:56320
	s_waitcnt vmcnt(8)
	s_waitcnt lgkmcnt(0)
	s_barrier
	s_setprio 1
	v_mfma_f32_16x16x32_bf16 v[60:63], v[132:135], v[176:179], v[60:63]
	v_mfma_f32_16x16x32_bf16 v[56:59], v[152:155], v[176:179], v[56:59]
	v_mfma_f32_16x16x32_bf16 v[44:47], v[132:135], v[184:187], v[44:47]
	v_mfma_f32_16x16x32_bf16 v[40:43], v[152:155], v[184:187], v[40:43]
	v_mfma_f32_16x16x32_bf16 v[28:31], v[132:135], v[192:195], v[28:31]
	v_mfma_f32_16x16x32_bf16 v[24:27], v[152:155], v[192:195], v[24:27]
	v_mfma_f32_16x16x32_bf16 v[12:15], v[132:135], v[200:203], v[12:15]
	v_mfma_f32_16x16x32_bf16 v[8:11], v[152:155], v[200:203], v[8:11]
	v_mfma_f32_16x16x32_bf16 v[60:63], v[148:151], v[180:183], v[60:63]
	v_mfma_f32_16x16x32_bf16 v[56:59], v[156:159], v[180:183], v[56:59]
	v_mfma_f32_16x16x32_bf16 v[44:47], v[148:151], v[188:191], v[44:47]
	v_mfma_f32_16x16x32_bf16 v[40:43], v[156:159], v[188:191], v[40:43]
	v_mfma_f32_16x16x32_bf16 v[28:31], v[148:151], v[196:199], v[28:31]
	v_mfma_f32_16x16x32_bf16 v[24:27], v[156:159], v[196:199], v[24:27]
	v_mfma_f32_16x16x32_bf16 v[12:15], v[148:151], v[204:207], v[12:15]
	v_mfma_f32_16x16x32_bf16 v[8:11], v[156:159], v[204:207], v[8:11]
	s_setprio 0
	s_setprio 1
	v_mfma_f32_16x16x32_bf16 v[52:55], v[160:163], v[176:179], v[52:55]
	v_mfma_f32_16x16x32_bf16 v[48:51], v[168:171], v[176:179], v[48:51]
	v_mfma_f32_16x16x32_bf16 v[36:39], v[160:163], v[184:187], v[36:39]
	v_mfma_f32_16x16x32_bf16 v[32:35], v[168:171], v[184:187], v[32:35]
	v_mfma_f32_16x16x32_bf16 v[20:23], v[160:163], v[192:195], v[20:23]
	v_mfma_f32_16x16x32_bf16 v[16:19], v[168:171], v[192:195], v[16:19]
	v_mfma_f32_16x16x32_bf16 v[4:7], v[160:163], v[200:203], v[4:7]
	v_mfma_f32_16x16x32_bf16 v[0:3], v[168:171], v[200:203], v[0:3]
	v_mfma_f32_16x16x32_bf16 v[52:55], v[164:167], v[180:183], v[52:55]
	v_mfma_f32_16x16x32_bf16 v[48:51], v[172:175], v[180:183], v[48:51]
	v_mfma_f32_16x16x32_bf16 v[36:39], v[164:167], v[188:191], v[36:39]
	v_mfma_f32_16x16x32_bf16 v[32:35], v[172:175], v[188:191], v[32:35]
	v_mfma_f32_16x16x32_bf16 v[20:23], v[164:167], v[196:199], v[20:23]
	v_mfma_f32_16x16x32_bf16 v[16:19], v[172:175], v[196:199], v[16:19]
	v_mfma_f32_16x16x32_bf16 v[4:7], v[164:167], v[204:207], v[4:7]
	v_mfma_f32_16x16x32_bf16 v[0:3], v[172:175], v[204:207], v[0:3]
	s_setprio 0
	s_barrier
	s_add_i32 s64, s64, 2
	s_add_u32 s51, s51, 0x10000
	s_addc_u32 s67, s67, 0
	s_add_u32 vcc_lo, vcc_lo, 0x100
	s_addc_u32 vcc_hi, vcc_hi, 0
	s_cmp_gt_u32 s64, 61
	s_cbranch_scc0 .LBB0_632
	s_and_b64 vcc, exec, s[26:27]
	s_cbranch_vccz .LBB0_635
	s_barrier

; #define PG8_STAGE(bufoff, gbase, voff) do { const __amdgpu_buffer_rsrc_t _rs = __builtin_amdgcn_make_buffer_rsrc((void*)(gbase), 0, 0x7fffffff, 0x00020000); _Pragma("unroll") for (int _i = 0; _i < 2; ++_i) \
;         __builtin_amdgcn_raw_ptr_buffer_load_lds(_rs, (LAS unsigned*)(lds + (bufoff) + ldsw + _i * 8192), 16, (int)(voff)[_i], 0, 0, 0); } while (0)
; #define PG8_WAIT_V(n) asm volatile("s_waitcnt vmcnt(" #n ")" ::: "memory")
; #define PG8_WAIT_L(n) asm volatile("s_waitcnt lgkmcnt(" #n ")" ::: "memory")
; #define PG8_BAR __builtin_amdgcn_s_barrier()
; #define PG8_SCHED __builtin_amdgcn_sched_barrier(0)
; template <class Epi, class Sched, bool F8 = false>
; __device__ __forceinline__ void gemm_phase(LAS unsigned char* lds, const int lda, const int ldb, const Sched& S, const Epi& E) {
;     ...
;             const char* a1 = cA + (size_t)(t + 1) * kstep;
;             const char* a2 = last ? nA : cA + (size_t)(t + 2) * kstep; const char* b2 = last ? nB : cB + (size_t)(t + 2) * kstepB;
;             const char* a3 = a2 + kstep; const char* b3 = b2 + kstepB;
;     ...
;             PG8_LDB(B0, 0, 0); PG8_LDB(B1, 0, 1); PG8_SCHED; PG8_LDA(At, 0, 0); PG8_STAGE(PG8_SA(1, 1), a1 + hstepA, voffA);
;             PG8_WAIT_V(8); PG8_WAIT_L(0); PG8_BAR; PG8_MMA(0, 0, At, B0); PG8_MMA(0, 1, At, B1); PG8_BAR; PG8_SCHED;
;             PG8_LDA(At, 0, 1); PG8_STAGE(PG8_SB(0, 0), b2, voffB); PG8_STAGE(PG8_SB(0, 1), b2 + hstepB, voffB); PG8_STAGE(PG8_SA(0, 0), a2, voffA);
;             PG8_WAIT_V(8); PG8_WAIT_L(0); PG8_BAR; PG8_MMA(1, 0, At, B0); PG8_MMA(1, 1, At, B1); PG8_BAR; PG8_SCHED;
.LBB0_778:
	s_add_u32 s4, s33, 0xfff00080
	s_addc_u32 s5, s43, -1
	s_cmp_eq_u32 s45, 60
	s_cselect_b32 s20, s46, s4
	s_cselect_b32 s7, s47, s5
	s_cselect_b32 s6, s49, s9
	s_cselect_b32 s16, s48, s8
	s_add_u32 s4, s20, 0x80
	s_addc_u32 s5, s7, 0
	s_and_b32 s13, s43, 0xffff
	s_mov_b32 s12, s33
	s_mov_b32 m0, s84
	s_nop 0
	buffer_load_dwordx4 v175, s[12:15], 0 offen lds
	s_mov_b32 m0, s86
	s_nop 0
	buffer_load_dwordx4 v179, s[12:15], 0 offen lds
	ds_read_b128 v[118:121], v194
	ds_read_b128 v[122:125], v194 offset:1024
	ds_read_b128 v[130:133], v194 offset:2048
	ds_read_b128 v[134:137], v194 offset:3072
	ds_read_b128 v[138:141], v195
	ds_read_b128 v[142:145], v195 offset:1024
	ds_read_b128 v[146:149], v195 offset:2048
	ds_read_b128 v[150:153], v195 offset:3072
	ds_read_b128 v[162:165], v196
	ds_read_b128 v[166:169], v196 offset:1024
	ds_read_b128 v[170:173], v196 offset:2048
	ds_read_b128 v[186:189], v196 offset:3072
	ds_read_b128 v[200:203], v196 offset:4096
	ds_read_b128 v[204:207], v196 offset:5120
	ds_read_b128 v[208:211], v196 offset:6144
	ds_read_b128 v[212:215], v196 offset:7168
	s_waitcnt vmcnt(8)
	s_waitcnt lgkmcnt(0)
	s_barrier
	s_setprio 1
	v_mfma_f32_16x16x32_bf16 v[158:161], v[118:121], v[162:165], v[158:161]
	v_mfma_f32_16x16x32_bf16 v[60:63], v[130:133], v[162:165], v[60:63]
	v_mfma_f32_16x16x32_bf16 v[154:157], v[118:121], v[170:173], v[154:157]
	v_mfma_f32_16x16x32_bf16 v[52:55], v[130:133], v[170:173], v[52:55]
	v_mfma_f32_16x16x32_bf16 v[114:117], v[118:121], v[200:203], v[114:117]
	v_mfma_f32_16x16x32_bf16 v[44:47], v[130:133], v[200:203], v[44:47]
	v_mfma_f32_16x16x32_bf16 v[108:111], v[118:121], v[208:211], v[110:113]
	v_mfma_f32_16x16x32_bf16 v[36:39], v[130:133], v[208:211], v[36:39]
	v_mfma_f32_16x16x32_bf16 v[158:161], v[122:125], v[166:169], v[158:161]
	v_mfma_f32_16x16x32_bf16 v[60:63], v[134:137], v[166:169], v[60:63]
	v_mfma_f32_16x16x32_bf16 v[154:157], v[122:125], v[186:189], v[154:157]
	v_mfma_f32_16x16x32_bf16 v[52:55], v[134:137], v[186:189], v[52:55]
	v_mfma_f32_16x16x32_bf16 v[114:117], v[122:125], v[204:207], v[114:117]
	v_mfma_f32_16x16x32_bf16 v[44:47], v[134:137], v[204:207], v[44:47]
	v_mfma_f32_16x16x32_bf16 v[108:111], v[122:125], v[212:215], v[108:111]
	v_mfma_f32_16x16x32_bf16 v[36:39], v[134:137], v[212:215], v[36:39]
	s_setprio 0
	s_setprio 1
	v_mfma_f32_16x16x32_bf16 v[104:107], v[138:141], v[162:165], v[104:107]
	v_mfma_f32_16x16x32_bf16 v[56:59], v[146:149], v[162:165], v[56:59]
	v_mfma_f32_16x16x32_bf16 v[126:129], v[138:141], v[170:173], v[126:129]
	v_mfma_f32_16x16x32_bf16 v[48:51], v[146:149], v[170:173], v[48:51]
	v_mfma_f32_16x16x32_bf16 v[100:103], v[138:141], v[200:203], v[100:103]
	v_mfma_f32_16x16x32_bf16 v[40:43], v[146:149], v[200:203], v[40:43]
	v_mfma_f32_16x16x32_bf16 v[96:99], v[138:141], v[208:211], v[96:99]
	v_mfma_f32_16x16x32_bf16 v[32:35], v[146:149], v[208:211], v[32:35]
	v_mfma_f32_16x16x32_bf16 v[104:107], v[142:145], v[166:169], v[104:107]
	v_mfma_f32_16x16x32_bf16 v[56:59], v[150:153], v[166:169], v[56:59]
	v_mfma_f32_16x16x32_bf16 v[126:129], v[142:145], v[186:189], v[126:129]
	v_mfma_f32_16x16x32_bf16 v[48:51], v[150:153], v[186:189], v[48:51]
	v_mfma_f32_16x16x32_bf16 v[100:103], v[142:145], v[204:207], v[100:103]
	v_mfma_f32_16x16x32_bf16 v[40:43], v[150:153], v[204:207], v[40:43]
	v_mfma_f32_16x16x32_bf16 v[96:99], v[142:145], v[212:215], v[96:99]
	v_mfma_f32_16x16x32_bf16 v[32:35], v[150:153], v[212:215], v[32:35]
	s_setprio 0
	s_barrier
	s_and_b32 s17, s6, 0xffff
	s_mov_b32 m0, s68
	s_mov_b32 s18, s14
	s_mov_b32 s19, s15
	s_add_u32 s12, s16, 0x4000
	buffer_load_dwordx4 v177, s[16:19], 0 offen lds
	s_mov_b32 m0, s69
	s_addc_u32 s13, s6, 0
	buffer_load_dwordx4 v193, s[16:19], 0 offen lds
	s_and_b32 s13, s13, 0xffff
	s_mov_b32 m0, s70
	s_and_b32 s21, s7, 0xffff
	buffer_load_dwordx4 v177, s[12:15], 0 offen lds
	s_mov_b32 m0, s71
	s_mov_b32 s22, s14
	buffer_load_dwordx4 v193, s[12:15], 0 offen lds
	s_mov_b32 s23, s15
	s_mov_b32 m0, s51
	s_nop 0
	buffer_load_dwordx4 v175, s[20:23], 0 offen lds
	s_mov_b32 m0, s72
	s_nop 0
	buffer_load_dwordx4 v179, s[20:23], 0 offen lds
	ds_read_b128 v[162:165], v196 offset:16384
	ds_read_b128 v[166:169], v196 offset:17408
	ds_read_b128 v[170:173], v196 offset:18432
	ds_read_b128 v[186:189], v196 offset:19456
	ds_read_b128 v[200:203], v196 offset:20480
	ds_read_b128 v[204:207], v196 offset:21504
	ds_read_b128 v[208:211], v196 offset:22528
	ds_read_b128 v[212:215], v196 offset:23552
	s_waitcnt vmcnt(8)
	s_waitcnt lgkmcnt(0)
	s_barrier
; #define PG8_STAGE(bufoff, gbase, voff) do { const __amdgpu_buffer_rsrc_t _rs = __builtin_amdgcn_make_buffer_rsrc((void*)(gbase), 0, 0x7fffffff, 0x00020000); _Pragma("unroll") for (int _i = 0; _i < 2; ++_i) \
;         __builtin_amdgcn_raw_ptr_buffer_load_lds(_rs, (LAS unsigned*)(lds + (bufoff) + ldsw + _i * 8192), 16, (int)(voff)[_i], 0, 0, 0); } while (0)
; #define PG8_WAIT_V(n) asm volatile("s_waitcnt vmcnt(" #n ")" ::: "memory")
; #define PG8_WAIT_L(n) asm volatile("s_waitcnt lgkmcnt(" #n ")" ::: "memory")
; #define PG8_BAR __builtin_amdgcn_s_barrier()
; #define PG8_SCHED __builtin_amdgcn_sched_barrier(0)
; template <class Epi, class Sched, bool F8 = false>
; __device__ __forceinline__ void gemm_phase(LAS unsigned char* lds, const int lda, const int ldb, const Sched& S, const Epi& E) {
;     ...
;             PG8_WAIT_V(8); PG8_WAIT_L(0); PG8_BAR; PG8_MMA(1, 0, At, B0); PG8_MMA(1, 1, At, B1); PG8_BAR; PG8_SCHED;
;             PG8_LDB(B0, 1, 0); PG8_LDB(B1, 1, 1); PG8_SCHED; PG8_LDA(At, 1, 0); PG8_STAGE(PG8_SA(0, 1), a2 + hstepA, voffA);
;             PG8_WAIT_V(8); PG8_WAIT_L(0); PG8_BAR; PG8_MMA(0, 0, At, B0); PG8_MMA(0, 1, At, B1); PG8_BAR; PG8_SCHED;
	s_setprio 1
	v_mfma_f32_16x16x32_bf16 v[92:95], v[118:121], v[162:165], v[92:95]
	v_mfma_f32_16x16x32_bf16 v[28:31], v[130:133], v[162:165], v[28:31]
	v_mfma_f32_16x16x32_bf16 v[84:87], v[118:121], v[170:173], v[84:87]
	v_mfma_f32_16x16x32_bf16 v[20:23], v[130:133], v[170:173], v[20:23]
	v_mfma_f32_16x16x32_bf16 v[76:79], v[118:121], v[200:203], v[76:79]
	v_mfma_f32_16x16x32_bf16 v[12:15], v[130:133], v[200:203], v[12:15]
	v_mfma_f32_16x16x32_bf16 v[72:75], v[118:121], v[208:211], v[72:75]
	v_mfma_f32_16x16x32_bf16 v[4:7], v[130:133], v[208:211], v[4:7]
	v_mfma_f32_16x16x32_bf16 v[92:95], v[122:125], v[166:169], v[92:95]
	v_mfma_f32_16x16x32_bf16 v[28:31], v[134:137], v[166:169], v[28:31]
	v_mfma_f32_16x16x32_bf16 v[84:87], v[122:125], v[186:189], v[84:87]
	v_mfma_f32_16x16x32_bf16 v[20:23], v[134:137], v[186:189], v[20:23]
	v_mfma_f32_16x16x32_bf16 v[76:79], v[122:125], v[204:207], v[76:79]
	v_mfma_f32_16x16x32_bf16 v[12:15], v[134:137], v[204:207], v[12:15]
	v_mfma_f32_16x16x32_bf16 v[72:75], v[122:125], v[212:215], v[72:75]
	v_mfma_f32_16x16x32_bf16 v[4:7], v[134:137], v[212:215], v[4:7]
	s_setprio 0
	s_setprio 1
	v_mfma_f32_16x16x32_bf16 v[88:91], v[138:141], v[162:165], v[88:91]
	v_mfma_f32_16x16x32_bf16 v[24:27], v[146:149], v[162:165], v[24:27]
	v_mfma_f32_16x16x32_bf16 v[80:83], v[138:141], v[170:173], v[80:83]
	v_mfma_f32_16x16x32_bf16 v[16:19], v[146:149], v[170:173], v[16:19]
	v_mfma_f32_16x16x32_bf16 v[68:71], v[138:141], v[200:203], v[68:71]
	v_mfma_f32_16x16x32_bf16 v[8:11], v[146:149], v[200:203], v[8:11]
	v_mfma_f32_16x16x32_bf16 v[64:67], v[138:141], v[208:211], v[64:67]
	v_mfma_f32_16x16x32_bf16 v[0:3], v[146:149], v[208:211], v[0:3]
	v_mfma_f32_16x16x32_bf16 v[88:91], v[142:145], v[166:169], v[88:91]
	v_mfma_f32_16x16x32_bf16 v[24:27], v[150:153], v[166:169], v[24:27]
	v_mfma_f32_16x16x32_bf16 v[80:83], v[142:145], v[186:189], v[80:83]
	v_mfma_f32_16x16x32_bf16 v[16:19], v[150:153], v[186:189], v[16:19]
	v_mfma_f32_16x16x32_bf16 v[68:71], v[142:145], v[204:207], v[68:71]
	v_mfma_f32_16x16x32_bf16 v[8:11], v[150:153], v[204:207], v[8:11]
	v_mfma_f32_16x16x32_bf16 v[64:67], v[142:145], v[212:215], v[64:67]
	v_mfma_f32_16x16x32_bf16 v[0:3], v[150:153], v[212:215], v[0:3]
	s_setprio 0
	s_barrier
	s_add_u32 s12, s20, 0x100000
	s_addc_u32 s7, s7, 0
	s_and_b32 s13, s7, 0xffff
	s_mov_b32 m0, s73
	s_nop 0
	buffer_load_dwordx4 v175, s[12:15], 0 offen lds
	s_mov_b32 m0, s74
	s_nop 0
	buffer_load_dwordx4 v179, s[12:15], 0 offen lds
	ds_read_b128 v[118:121], v197
	ds_read_b128 v[122:125], v197 offset:1024
	ds_read_b128 v[130:133], v197 offset:2048
	ds_read_b128 v[134:137], v197 offset:3072
	ds_read_b128 v[138:141], v198
	ds_read_b128 v[142:145], v198 offset:1024
	ds_read_b128 v[146:149], v198 offset:2048
	ds_read_b128 v[150:153], v198 offset:3072
	ds_read_b128 v[162:165], v196 offset:32768
	ds_read_b128 v[166:169], v196 offset:33792
	ds_read_b128 v[170:173], v196 offset:34816
	ds_read_b128 v[186:189], v196 offset:35840
	ds_read_b128 v[200:203], v196 offset:36864
	ds_read_b128 v[204:207], v196 offset:37888
	ds_read_b128 v[208:211], v196 offset:38912
	ds_read_b128 v[212:215], v196 offset:39936
	s_waitcnt vmcnt(8)
	s_waitcnt lgkmcnt(0)
	s_barrier
	s_setprio 1
	v_mfma_f32_16x16x32_bf16 v[158:161], v[118:121], v[162:165], v[158:161]
	v_mfma_f32_16x16x32_bf16 v[60:63], v[130:133], v[162:165], v[60:63]
	v_mfma_f32_16x16x32_bf16 v[154:157], v[118:121], v[170:173], v[154:157]
	v_mfma_f32_16x16x32_bf16 v[52:55], v[130:133], v[170:173], v[52:55]
	v_mfma_f32_16x16x32_bf16 v[112:115], v[118:121], v[200:203], v[114:117]
	v_mfma_f32_16x16x32_bf16 v[44:47], v[130:133], v[200:203], v[44:47]
	v_mfma_f32_16x16x32_bf16 v[108:111], v[118:121], v[208:211], v[108:111]
	v_mfma_f32_16x16x32_bf16 v[36:39], v[130:133], v[208:211], v[36:39]
	v_mfma_f32_16x16x32_bf16 v[158:161], v[122:125], v[166:169], v[158:161]
	v_mfma_f32_16x16x32_bf16 v[60:63], v[134:137], v[166:169], v[60:63]
	v_mfma_f32_16x16x32_bf16 v[154:157], v[122:125], v[186:189], v[154:157]
	v_mfma_f32_16x16x32_bf16 v[52:55], v[134:137], v[186:189], v[52:55]
	v_mfma_f32_16x16x32_bf16 v[114:117], v[122:125], v[204:207], v[112:115]
	v_mfma_f32_16x16x32_bf16 v[44:47], v[134:137], v[204:207], v[44:47]
	v_mfma_f32_16x16x32_bf16 v[110:113], v[122:125], v[212:215], v[108:111]
	v_mfma_f32_16x16x32_bf16 v[36:39], v[134:137], v[212:215], v[36:39]
	s_setprio 0
	s_setprio 1
	v_mfma_f32_16x16x32_bf16 v[104:107], v[138:141], v[162:165], v[104:107]
	v_mfma_f32_16x16x32_bf16 v[56:59], v[146:149], v[162:165], v[56:59]
	v_mfma_f32_16x16x32_bf16 v[126:129], v[138:141], v[170:173], v[126:129]
	v_mfma_f32_16x16x32_bf16 v[48:51], v[146:149], v[170:173], v[48:51]
	v_mfma_f32_16x16x32_bf16 v[100:103], v[138:141], v[200:203], v[100:103]
	v_mfma_f32_16x16x32_bf16 v[40:43], v[146:149], v[200:203], v[40:43]
	v_mfma_f32_16x16x32_bf16 v[96:99], v[138:141], v[208:211], v[96:99]
	v_mfma_f32_16x16x32_bf16 v[32:35], v[146:149], v[208:211], v[32:35]
	v_mfma_f32_16x16x32_bf16 v[104:107], v[142:145], v[166:169], v[104:107]
	v_mfma_f32_16x16x32_bf16 v[56:59], v[150:153], v[166:169], v[56:59]
	v_mfma_f32_16x16x32_bf16 v[126:129], v[142:145], v[186:189], v[126:129]
	v_mfma_f32_16x16x32_bf16 v[48:51], v[150:153], v[186:189], v[48:51]
	v_mfma_f32_16x16x32_bf16 v[100:103], v[142:145], v[204:207], v[100:103]
	v_mfma_f32_16x16x32_bf16 v[40:43], v[150:153], v[204:207], v[40:43]
	v_mfma_f32_16x16x32_bf16 v[96:99], v[142:145], v[212:215], v[96:99]
	v_mfma_f32_16x16x32_bf16 v[32:35], v[150:153], v[212:215], v[32:35]
	s_setprio 0
	s_barrier
; #define PG8_STAGE(bufoff, gbase, voff) do { const __amdgpu_buffer_rsrc_t _rs = __builtin_amdgcn_make_buffer_rsrc((void*)(gbase), 0, 0x7fffffff, 0x00020000); _Pragma("unroll") for (int _i = 0; _i < 2; ++_i) \
;         __builtin_amdgcn_raw_ptr_buffer_load_lds(_rs, (LAS unsigned*)(lds + (bufoff) + ldsw + _i * 8192), 16, (int)(voff)[_i], 0, 0, 0); } while (0)
; #define PG8_WAIT_V(n) asm volatile("s_waitcnt vmcnt(" #n ")" ::: "memory")
; #define PG8_WAIT_L(n) asm volatile("s_waitcnt lgkmcnt(" #n ")" ::: "memory")
; #define PG8_BAR __builtin_amdgcn_s_barrier()
; #define PG8_SCHED __builtin_amdgcn_sched_barrier(0)
; template <class Epi, class Sched, bool F8 = false>
; __device__ __forceinline__ void gemm_phase(LAS unsigned char* lds, const int lda, const int ldb, const Sched& S, const Epi& E) {
;     ...
;         for (int t = 0; t < nt; t += 2) {
;     ...
;             PG8_LDA(At, 1, 1); PG8_STAGE(PG8_SB(1, 0), b3, voffB); PG8_STAGE(PG8_SB(1, 1), b3 + hstepB, voffB); PG8_STAGE(PG8_SA(1, 0), a3, voffA);
;             PG8_WAIT_V(8); PG8_WAIT_L(0); PG8_BAR; PG8_MMA(1, 0, At, B0); PG8_MMA(1, 1, At, B1); PG8_BAR; PG8_SCHED;
	s_add_u32 s12, s16, 0x8000
	s_addc_u32 s7, s6, 0
	s_mov_b32 m0, s78
	s_and_b32 s13, s7, 0xffff
	buffer_load_dwordx4 v177, s[12:15], 0 offen lds
	s_mov_b32 m0, s79
	s_mov_b32 s7, s15
	buffer_load_dwordx4 v193, s[12:15], 0 offen lds
	s_add_u32 s12, s16, 0xc000
	s_addc_u32 s6, s6, 0
	s_and_b32 s13, s6, 0xffff
	s_mov_b32 m0, s82
	s_and_b32 s5, s5, 0xffff
	buffer_load_dwordx4 v177, s[12:15], 0 offen lds
	s_mov_b32 m0, s83
	s_mov_b32 s6, s14
	buffer_load_dwordx4 v193, s[12:15], 0 offen lds
	s_mov_b32 m0, s80
	s_nop 0
	buffer_load_dwordx4 v175, s[4:7], 0 offen lds
	s_mov_b32 m0, s81
	s_nop 0
	buffer_load_dwordx4 v179, s[4:7], 0 offen lds
	ds_read_b128 v[162:165], v196 offset:49152
	ds_read_b128 v[166:169], v196 offset:50176
	ds_read_b128 v[170:173], v196 offset:51200
	ds_read_b128 v[186:189], v196 offset:52224
	ds_read_b128 v[200:203], v196 offset:53248
	ds_read_b128 v[204:207], v196 offset:54272
	ds_read_b128 v[208:211], v196 offset:55296
	ds_read_b128 v[212:215], v196 offset:56320
	s_waitcnt vmcnt(8)
	s_waitcnt lgkmcnt(0)
	s_barrier
	s_setprio 1
	v_mfma_f32_16x16x32_bf16 v[92:95], v[118:121], v[162:165], v[92:95]
	v_mfma_f32_16x16x32_bf16 v[28:31], v[130:133], v[162:165], v[28:31]
	v_mfma_f32_16x16x32_bf16 v[84:87], v[118:121], v[170:173], v[84:87]
	v_mfma_f32_16x16x32_bf16 v[20:23], v[130:133], v[170:173], v[20:23]
	v_mfma_f32_16x16x32_bf16 v[76:79], v[118:121], v[200:203], v[76:79]
	v_mfma_f32_16x16x32_bf16 v[12:15], v[130:133], v[200:203], v[12:15]
	v_mfma_f32_16x16x32_bf16 v[72:75], v[118:121], v[208:211], v[72:75]
	v_mfma_f32_16x16x32_bf16 v[4:7], v[130:133], v[208:211], v[4:7]
	v_mfma_f32_16x16x32_bf16 v[92:95], v[122:125], v[166:169], v[92:95]
	v_mfma_f32_16x16x32_bf16 v[28:31], v[134:137], v[166:169], v[28:31]
	v_mfma_f32_16x16x32_bf16 v[84:87], v[122:125], v[186:189], v[84:87]
	v_mfma_f32_16x16x32_bf16 v[20:23], v[134:137], v[186:189], v[20:23]
	v_mfma_f32_16x16x32_bf16 v[76:79], v[122:125], v[204:207], v[76:79]
	v_mfma_f32_16x16x32_bf16 v[12:15], v[134:137], v[204:207], v[12:15]
	v_mfma_f32_16x16x32_bf16 v[72:75], v[122:125], v[212:215], v[72:75]
	v_mfma_f32_16x16x32_bf16 v[4:7], v[134:137], v[212:215], v[4:7]
	s_setprio 0
	s_setprio 1
	v_mfma_f32_16x16x32_bf16 v[88:91], v[138:141], v[162:165], v[88:91]
	v_mfma_f32_16x16x32_bf16 v[24:27], v[146:149], v[162:165], v[24:27]
	v_mfma_f32_16x16x32_bf16 v[80:83], v[138:141], v[170:173], v[80:83]
	v_mfma_f32_16x16x32_bf16 v[16:19], v[146:149], v[170:173], v[16:19]
	v_mfma_f32_16x16x32_bf16 v[68:71], v[138:141], v[200:203], v[68:71]
	v_mfma_f32_16x16x32_bf16 v[8:11], v[146:149], v[200:203], v[8:11]
	v_mfma_f32_16x16x32_bf16 v[64:67], v[138:141], v[208:211], v[64:67]
	v_mfma_f32_16x16x32_bf16 v[0:3], v[146:149], v[208:211], v[0:3]
	v_mfma_f32_16x16x32_bf16 v[88:91], v[142:145], v[166:169], v[88:91]
	v_mfma_f32_16x16x32_bf16 v[24:27], v[150:153], v[166:169], v[24:27]
	v_mfma_f32_16x16x32_bf16 v[80:83], v[142:145], v[186:189], v[80:83]
	v_mfma_f32_16x16x32_bf16 v[16:19], v[150:153], v[186:189], v[16:19]
	v_mfma_f32_16x16x32_bf16 v[68:71], v[142:145], v[204:207], v[68:71]
	v_mfma_f32_16x16x32_bf16 v[8:11], v[150:153], v[204:207], v[8:11]
	v_mfma_f32_16x16x32_bf16 v[64:67], v[142:145], v[212:215], v[64:67]
	v_mfma_f32_16x16x32_bf16 v[0:3], v[150:153], v[212:215], v[0:3]
	s_setprio 0
	s_barrier
	s_add_i32 s45, s45, 2
	s_add_u32 s8, s8, 0x10000
	s_addc_u32 s9, s9, 0
	s_add_u32 s33, s33, 0x100
	s_addc_u32 s43, s43, 0
	s_cmp_gt_u32 s45, 61
	s_cbranch_scc0 .LBB0_778
	s_and_b64 vcc, exec, s[40:41]
	s_cbranch_vccz .LBB0_781
	s_barrier

; #define PG8_STAGE(bufoff, gbase, voff) do { const __amdgpu_buffer_rsrc_t _rs = __builtin_amdgcn_make_buffer_rsrc((void*)(gbase), 0, 0x7fffffff, 0x00020000); _Pragma("unroll") for (int _i = 0; _i < 2; ++_i) \
;         __builtin_amdgcn_raw_ptr_buffer_load_lds(_rs, (LAS unsigned*)(lds + (bufoff) + ldsw + _i * 8192), 16, (int)(voff)[_i], 0, 0, 0); } while (0)
; #define PG8_WAIT_V(n) asm volatile("s_waitcnt vmcnt(" #n ")" ::: "memory")
; #define PG8_WAIT_L(n) asm volatile("s_waitcnt lgkmcnt(" #n ")" ::: "memory")
; #define PG8_BAR __builtin_amdgcn_s_barrier()
; #define PG8_SCHED __builtin_amdgcn_sched_barrier(0)
; template <class Epi, class Sched, bool F8 = false>
; __device__ __forceinline__ void gemm_phase(LAS unsigned char* lds, const int lda, const int ldb, const Sched& S, const Epi& E) {
;     ...
;             const bool last = (t == nt - 2);
;             const char* a1 = cA + (size_t)(t + 1) * kstep;
;             const char* a2 = last ? nA : cA + (size_t)(t + 2) * kstep; const char* b2 = last ? nB : cB + (size_t)(t + 2) * kstepB;
;             const char* a3 = a2 + kstep; const char* b3 = b2 + kstepB;
;     ...
;             PG8_LDB(B0, 0, 0); PG8_LDB(B1, 0, 1); PG8_SCHED; PG8_LDA(At, 0, 0); PG8_STAGE(PG8_SA(1, 1), a1 + hstepA, voffA);
;             PG8_WAIT_V(8); PG8_WAIT_L(0); PG8_BAR; PG8_MMA(0, 0, At, B0); PG8_MMA(0, 1, At, B1); PG8_BAR; PG8_SCHED;
;             PG8_LDA(At, 0, 1); PG8_STAGE(PG8_SB(0, 0), b2, voffB); PG8_STAGE(PG8_SB(0, 1), b2 + hstepB, voffB); PG8_STAGE(PG8_SA(0, 0), a2, voffA);
;             PG8_WAIT_V(8); PG8_WAIT_L(0); PG8_BAR; PG8_MMA(1, 0, At, B0); PG8_MMA(1, 1, At, B1); PG8_BAR; PG8_SCHED;
.LBB0_935:
	s_add_u32 s4, s91, 0xffd50080
	s_addc_u32 s5, s92, -1
	s_cmpk_eq_i32 s64, 0xa8
	s_cselect_b32 s20, s44, s4
	s_cselect_b32 s15, s45, s5
	s_cselect_b32 s14, s47, s90
	s_cselect_b32 s16, s46, s89
	s_add_u32 s12, s20, 0x80
	s_addc_u32 s13, s15, 0
	s_and_b32 s5, s92, 0xffff
	s_mov_b32 s4, s91
	s_mov_b32 m0, s79
	s_nop 0
	buffer_load_dwordx4 v128, s[4:7], 0 offen lds
	s_mov_b32 m0, s80
	s_nop 0
	buffer_load_dwordx4 v130, s[4:7], 0 offen lds
	ds_read_b128 v[136:139], v142
	ds_read_b128 v[148:151], v142 offset:1024
	ds_read_b128 v[152:155], v142 offset:2048
	ds_read_b128 v[156:159], v142 offset:3072
	ds_read_b128 v[160:163], v143
	ds_read_b128 v[164:167], v143 offset:1024
	ds_read_b128 v[168:171], v143 offset:2048
	ds_read_b128 v[180:183], v143 offset:3072
	ds_read_b128 v[184:187], v144
	ds_read_b128 v[188:191], v144 offset:1024
	ds_read_b128 v[194:197], v144 offset:2048
	ds_read_b128 v[198:201], v144 offset:3072
	ds_read_b128 v[202:205], v144 offset:4096
	ds_read_b128 v[206:209], v144 offset:5120
	ds_read_b128 v[210:213], v144 offset:6144
	ds_read_b128 v[214:217], v144 offset:7168
	s_waitcnt vmcnt(8)
	s_waitcnt lgkmcnt(0)
	s_barrier
	s_setprio 1
	v_mfma_f32_16x16x32_bf16 v[124:127], v[136:139], v[184:187], v[124:127]
	v_mfma_f32_16x16x32_bf16 v[120:123], v[152:155], v[184:187], v[120:123]
	v_mfma_f32_16x16x32_bf16 v[108:111], v[136:139], v[194:197], v[108:111]
	v_mfma_f32_16x16x32_bf16 v[104:107], v[152:155], v[194:197], v[104:107]
	v_mfma_f32_16x16x32_bf16 v[92:95], v[136:139], v[202:205], v[92:95]
	v_mfma_f32_16x16x32_bf16 v[88:91], v[152:155], v[202:205], v[88:91]
	v_mfma_f32_16x16x32_bf16 v[76:79], v[136:139], v[210:213], v[76:79]
	v_mfma_f32_16x16x32_bf16 v[72:75], v[152:155], v[210:213], v[72:75]
	v_mfma_f32_16x16x32_bf16 v[124:127], v[148:151], v[188:191], v[124:127]
	v_mfma_f32_16x16x32_bf16 v[120:123], v[156:159], v[188:191], v[120:123]
	v_mfma_f32_16x16x32_bf16 v[108:111], v[148:151], v[198:201], v[108:111]
	v_mfma_f32_16x16x32_bf16 v[104:107], v[156:159], v[198:201], v[104:107]
	v_mfma_f32_16x16x32_bf16 v[92:95], v[148:151], v[206:209], v[92:95]
	v_mfma_f32_16x16x32_bf16 v[88:91], v[156:159], v[206:209], v[88:91]
	v_mfma_f32_16x16x32_bf16 v[76:79], v[148:151], v[214:217], v[76:79]
	v_mfma_f32_16x16x32_bf16 v[72:75], v[156:159], v[214:217], v[72:75]
	s_setprio 0
	s_setprio 1
	v_mfma_f32_16x16x32_bf16 v[116:119], v[160:163], v[184:187], v[116:119]
	v_mfma_f32_16x16x32_bf16 v[112:115], v[168:171], v[184:187], v[112:115]
	v_mfma_f32_16x16x32_bf16 v[100:103], v[160:163], v[194:197], v[100:103]
	v_mfma_f32_16x16x32_bf16 v[96:99], v[168:171], v[194:197], v[96:99]
	v_mfma_f32_16x16x32_bf16 v[84:87], v[160:163], v[202:205], v[84:87]
	v_mfma_f32_16x16x32_bf16 v[80:83], v[168:171], v[202:205], v[80:83]
	v_mfma_f32_16x16x32_bf16 v[68:71], v[160:163], v[210:213], v[68:71]
	v_mfma_f32_16x16x32_bf16 v[64:67], v[168:171], v[210:213], v[64:67]
	v_mfma_f32_16x16x32_bf16 v[116:119], v[164:167], v[188:191], v[116:119]
	v_mfma_f32_16x16x32_bf16 v[112:115], v[180:183], v[188:191], v[112:115]
	v_mfma_f32_16x16x32_bf16 v[100:103], v[164:167], v[198:201], v[100:103]
	v_mfma_f32_16x16x32_bf16 v[96:99], v[180:183], v[198:201], v[96:99]
	v_mfma_f32_16x16x32_bf16 v[84:87], v[164:167], v[206:209], v[84:87]
	v_mfma_f32_16x16x32_bf16 v[80:83], v[180:183], v[206:209], v[80:83]
	v_mfma_f32_16x16x32_bf16 v[68:71], v[164:167], v[214:217], v[68:71]
	v_mfma_f32_16x16x32_bf16 v[64:67], v[180:183], v[214:217], v[64:67]
	s_setprio 0
	s_barrier
	s_and_b32 s17, s14, 0xffff
	s_mov_b32 m0, s49
	s_mov_b32 s18, s6
	s_mov_b32 s19, s7
	s_add_u32 s4, s16, 0x4000
	buffer_load_dwordx4 v129, s[16:19], 0 offen lds
	s_mov_b32 m0, s50
	s_addc_u32 s5, s14, 0
	buffer_load_dwordx4 v131, s[16:19], 0 offen lds
	s_and_b32 s5, s5, 0xffff
	s_mov_b32 m0, s51
	s_and_b32 s21, s15, 0xffff
	buffer_load_dwordx4 v129, s[4:7], 0 offen lds
	s_mov_b32 m0, s52
	s_mov_b32 s22, s6
	buffer_load_dwordx4 v131, s[4:7], 0 offen lds
	s_mov_b32 s23, s7
	s_mov_b32 m0, s48
	s_nop 0
	buffer_load_dwordx4 v128, s[20:23], 0 offen lds
	s_mov_b32 m0, s53
	s_nop 0
	buffer_load_dwordx4 v130, s[20:23], 0 offen lds
	ds_read_b128 v[184:187], v144 offset:16384
	ds_read_b128 v[188:191], v144 offset:17408
	ds_read_b128 v[194:197], v144 offset:18432
	ds_read_b128 v[198:201], v144 offset:19456
	ds_read_b128 v[202:205], v144 offset:20480
	ds_read_b128 v[206:209], v144 offset:21504
	ds_read_b128 v[210:213], v144 offset:22528
	ds_read_b128 v[214:217], v144 offset:23552
	s_waitcnt vmcnt(8)
	s_waitcnt lgkmcnt(0)
	s_barrier
; #define PG8_STAGE(bufoff, gbase, voff) do { const __amdgpu_buffer_rsrc_t _rs = __builtin_amdgcn_make_buffer_rsrc((void*)(gbase), 0, 0x7fffffff, 0x00020000); _Pragma("unroll") for (int _i = 0; _i < 2; ++_i) \
;         __builtin_amdgcn_raw_ptr_buffer_load_lds(_rs, (LAS unsigned*)(lds + (bufoff) + ldsw + _i * 8192), 16, (int)(voff)[_i], 0, 0, 0); } while (0)
; #define PG8_WAIT_V(n) asm volatile("s_waitcnt vmcnt(" #n ")" ::: "memory")
; #define PG8_WAIT_L(n) asm volatile("s_waitcnt lgkmcnt(" #n ")" ::: "memory")
; #define PG8_BAR __builtin_amdgcn_s_barrier()
; #define PG8_SCHED __builtin_amdgcn_sched_barrier(0)
; template <class Epi, class Sched, bool F8 = false>
; __device__ __forceinline__ void gemm_phase(LAS unsigned char* lds, const int lda, const int ldb, const Sched& S, const Epi& E) {
;     ...
;             PG8_WAIT_V(8); PG8_WAIT_L(0); PG8_BAR; PG8_MMA(1, 0, At, B0); PG8_MMA(1, 1, At, B1); PG8_BAR; PG8_SCHED;
;             PG8_LDB(B0, 1, 0); PG8_LDB(B1, 1, 1); PG8_SCHED; PG8_LDA(At, 1, 0); PG8_STAGE(PG8_SA(0, 1), a2 + hstepA, voffA);
;             PG8_WAIT_V(8); PG8_WAIT_L(0); PG8_BAR; PG8_MMA(0, 0, At, B0); PG8_MMA(0, 1, At, B1); PG8_BAR; PG8_SCHED;
	s_setprio 1
	v_mfma_f32_16x16x32_bf16 v[60:63], v[136:139], v[184:187], v[60:63]
	v_mfma_f32_16x16x32_bf16 v[56:59], v[152:155], v[184:187], v[56:59]
	v_mfma_f32_16x16x32_bf16 v[44:47], v[136:139], v[194:197], v[44:47]
	v_mfma_f32_16x16x32_bf16 v[40:43], v[152:155], v[194:197], v[40:43]
	v_mfma_f32_16x16x32_bf16 v[28:31], v[136:139], v[202:205], v[28:31]
	v_mfma_f32_16x16x32_bf16 v[24:27], v[152:155], v[202:205], v[24:27]
	v_mfma_f32_16x16x32_bf16 v[12:15], v[136:139], v[210:213], v[12:15]
	v_mfma_f32_16x16x32_bf16 v[8:11], v[152:155], v[210:213], v[8:11]
	v_mfma_f32_16x16x32_bf16 v[60:63], v[148:151], v[188:191], v[60:63]
	v_mfma_f32_16x16x32_bf16 v[56:59], v[156:159], v[188:191], v[56:59]
	v_mfma_f32_16x16x32_bf16 v[44:47], v[148:151], v[198:201], v[44:47]
	v_mfma_f32_16x16x32_bf16 v[40:43], v[156:159], v[198:201], v[40:43]
	v_mfma_f32_16x16x32_bf16 v[28:31], v[148:151], v[206:209], v[28:31]
	v_mfma_f32_16x16x32_bf16 v[24:27], v[156:159], v[206:209], v[24:27]
	v_mfma_f32_16x16x32_bf16 v[12:15], v[148:151], v[214:217], v[12:15]
	v_mfma_f32_16x16x32_bf16 v[8:11], v[156:159], v[214:217], v[8:11]
	s_setprio 0
	s_setprio 1
	v_mfma_f32_16x16x32_bf16 v[52:55], v[160:163], v[184:187], v[52:55]
	v_mfma_f32_16x16x32_bf16 v[48:51], v[168:171], v[184:187], v[48:51]
	v_mfma_f32_16x16x32_bf16 v[36:39], v[160:163], v[194:197], v[36:39]
	v_mfma_f32_16x16x32_bf16 v[32:35], v[168:171], v[194:197], v[32:35]
	v_mfma_f32_16x16x32_bf16 v[20:23], v[160:163], v[202:205], v[20:23]
	v_mfma_f32_16x16x32_bf16 v[16:19], v[168:171], v[202:205], v[16:19]
	v_mfma_f32_16x16x32_bf16 v[4:7], v[160:163], v[210:213], v[4:7]
	v_mfma_f32_16x16x32_bf16 v[0:3], v[168:171], v[210:213], v[0:3]
	v_mfma_f32_16x16x32_bf16 v[52:55], v[164:167], v[188:191], v[52:55]
	v_mfma_f32_16x16x32_bf16 v[48:51], v[180:183], v[188:191], v[48:51]
	v_mfma_f32_16x16x32_bf16 v[36:39], v[164:167], v[198:201], v[36:39]
	v_mfma_f32_16x16x32_bf16 v[32:35], v[180:183], v[198:201], v[32:35]
	v_mfma_f32_16x16x32_bf16 v[20:23], v[164:167], v[206:209], v[20:23]
	v_mfma_f32_16x16x32_bf16 v[16:19], v[180:183], v[206:209], v[16:19]
	v_mfma_f32_16x16x32_bf16 v[4:7], v[164:167], v[214:217], v[4:7]
	v_mfma_f32_16x16x32_bf16 v[0:3], v[180:183], v[214:217], v[0:3]
	s_setprio 0
	s_barrier
	s_add_u32 s4, s20, 0x2b0000
	s_addc_u32 s5, s15, 0
	s_and_b32 s5, s5, 0xffff
	s_mov_b32 m0, s61
	s_nop 0
	buffer_load_dwordx4 v128, s[4:7], 0 offen lds
	s_mov_b32 m0, s66
	s_nop 0
	buffer_load_dwordx4 v130, s[4:7], 0 offen lds
	ds_read_b128 v[136:139], v145
	ds_read_b128 v[148:151], v145 offset:1024
	ds_read_b128 v[152:155], v145 offset:2048
	ds_read_b128 v[156:159], v145 offset:3072
	ds_read_b128 v[160:163], v146
	ds_read_b128 v[164:167], v146 offset:1024
	ds_read_b128 v[168:171], v146 offset:2048
	ds_read_b128 v[180:183], v146 offset:3072
	ds_read_b128 v[184:187], v144 offset:32768
	ds_read_b128 v[188:191], v144 offset:33792
	ds_read_b128 v[194:197], v144 offset:34816
	ds_read_b128 v[198:201], v144 offset:35840
	ds_read_b128 v[202:205], v144 offset:36864
	ds_read_b128 v[206:209], v144 offset:37888
	ds_read_b128 v[210:213], v144 offset:38912
	ds_read_b128 v[214:217], v144 offset:39936
	s_waitcnt vmcnt(8)
	s_waitcnt lgkmcnt(0)
	s_barrier
	s_setprio 1
	v_mfma_f32_16x16x32_bf16 v[124:127], v[136:139], v[184:187], v[124:127]
	v_mfma_f32_16x16x32_bf16 v[120:123], v[152:155], v[184:187], v[120:123]
	v_mfma_f32_16x16x32_bf16 v[108:111], v[136:139], v[194:197], v[108:111]
	v_mfma_f32_16x16x32_bf16 v[104:107], v[152:155], v[194:197], v[104:107]
	v_mfma_f32_16x16x32_bf16 v[92:95], v[136:139], v[202:205], v[92:95]
	v_mfma_f32_16x16x32_bf16 v[88:91], v[152:155], v[202:205], v[88:91]
	v_mfma_f32_16x16x32_bf16 v[76:79], v[136:139], v[210:213], v[76:79]
	v_mfma_f32_16x16x32_bf16 v[72:75], v[152:155], v[210:213], v[72:75]
	v_mfma_f32_16x16x32_bf16 v[124:127], v[148:151], v[188:191], v[124:127]
	v_mfma_f32_16x16x32_bf16 v[120:123], v[156:159], v[188:191], v[120:123]
	v_mfma_f32_16x16x32_bf16 v[108:111], v[148:151], v[198:201], v[108:111]
	v_mfma_f32_16x16x32_bf16 v[104:107], v[156:159], v[198:201], v[104:107]
	v_mfma_f32_16x16x32_bf16 v[92:95], v[148:151], v[206:209], v[92:95]
	v_mfma_f32_16x16x32_bf16 v[88:91], v[156:159], v[206:209], v[88:91]
	v_mfma_f32_16x16x32_bf16 v[76:79], v[148:151], v[214:217], v[76:79]
	v_mfma_f32_16x16x32_bf16 v[72:75], v[156:159], v[214:217], v[72:75]
	s_setprio 0
	s_setprio 1
	v_mfma_f32_16x16x32_bf16 v[116:119], v[160:163], v[184:187], v[116:119]
	v_mfma_f32_16x16x32_bf16 v[112:115], v[168:171], v[184:187], v[112:115]
	v_mfma_f32_16x16x32_bf16 v[100:103], v[160:163], v[194:197], v[100:103]
	v_mfma_f32_16x16x32_bf16 v[96:99], v[168:171], v[194:197], v[96:99]
	v_mfma_f32_16x16x32_bf16 v[84:87], v[160:163], v[202:205], v[84:87]
	v_mfma_f32_16x16x32_bf16 v[80:83], v[168:171], v[202:205], v[80:83]
	v_mfma_f32_16x16x32_bf16 v[68:71], v[160:163], v[210:213], v[68:71]
	v_mfma_f32_16x16x32_bf16 v[64:67], v[168:171], v[210:213], v[64:67]
	v_mfma_f32_16x16x32_bf16 v[116:119], v[164:167], v[188:191], v[116:119]
	v_mfma_f32_16x16x32_bf16 v[112:115], v[180:183], v[188:191], v[112:115]
	v_mfma_f32_16x16x32_bf16 v[100:103], v[164:167], v[198:201], v[100:103]
	v_mfma_f32_16x16x32_bf16 v[96:99], v[180:183], v[198:201], v[96:99]
	v_mfma_f32_16x16x32_bf16 v[84:87], v[164:167], v[206:209], v[84:87]
	v_mfma_f32_16x16x32_bf16 v[80:83], v[180:183], v[206:209], v[80:83]
	v_mfma_f32_16x16x32_bf16 v[68:71], v[164:167], v[214:217], v[68:71]
	v_mfma_f32_16x16x32_bf16 v[64:67], v[180:183], v[214:217], v[64:67]
	s_setprio 0
	s_barrier
; #define PG8_STAGE(bufoff, gbase, voff) do { const __amdgpu_buffer_rsrc_t _rs = __builtin_amdgcn_make_buffer_rsrc((void*)(gbase), 0, 0x7fffffff, 0x00020000); _Pragma("unroll") for (int _i = 0; _i < 2; ++_i) \
;         __builtin_amdgcn_raw_ptr_buffer_load_lds(_rs, (LAS unsigned*)(lds + (bufoff) + ldsw + _i * 8192), 16, (int)(voff)[_i], 0, 0, 0); } while (0)
; #define PG8_WAIT_V(n) asm volatile("s_waitcnt vmcnt(" #n ")" ::: "memory")
; #define PG8_WAIT_L(n) asm volatile("s_waitcnt lgkmcnt(" #n ")" ::: "memory")
; #define PG8_BAR __builtin_amdgcn_s_barrier()
; #define PG8_SCHED __builtin_amdgcn_sched_barrier(0)
; template <class Epi, class Sched, bool F8 = false>
; __device__ __forceinline__ void gemm_phase(LAS unsigned char* lds, const int lda, const int ldb, const Sched& S, const Epi& E) {
;     ...
;         for (int t = 0; t < nt; t += 2) {
;     ...
;             PG8_LDA(At, 1, 1); PG8_STAGE(PG8_SB(1, 0), b3, voffB); PG8_STAGE(PG8_SB(1, 1), b3 + hstepB, voffB); PG8_STAGE(PG8_SA(1, 0), a3, voffA);
;             PG8_WAIT_V(8); PG8_WAIT_L(0); PG8_BAR; PG8_MMA(1, 0, At, B0); PG8_MMA(1, 1, At, B1); PG8_BAR; PG8_SCHED;
	s_add_u32 s4, s16, 0x8000
	s_addc_u32 s5, s14, 0
	s_mov_b32 m0, s73
	s_and_b32 s5, s5, 0xffff
	buffer_load_dwordx4 v129, s[4:7], 0 offen lds
	s_mov_b32 m0, s74
	s_mov_b32 s15, s7
	buffer_load_dwordx4 v131, s[4:7], 0 offen lds
	s_add_u32 s4, s16, 0xc000
	s_addc_u32 s5, s14, 0
	s_and_b32 s5, s5, 0xffff
	s_mov_b32 m0, s77
	s_and_b32 s13, s13, 0xffff
	buffer_load_dwordx4 v129, s[4:7], 0 offen lds
	s_mov_b32 m0, s78
	s_mov_b32 s14, s6
	buffer_load_dwordx4 v131, s[4:7], 0 offen lds
	s_mov_b32 m0, s75
	s_nop 0
	buffer_load_dwordx4 v128, s[12:15], 0 offen lds
	s_mov_b32 m0, s76
	s_nop 0
	buffer_load_dwordx4 v130, s[12:15], 0 offen lds
	ds_read_b128 v[184:187], v144 offset:49152
	ds_read_b128 v[188:191], v144 offset:50176
	ds_read_b128 v[194:197], v144 offset:51200
	ds_read_b128 v[198:201], v144 offset:52224
	ds_read_b128 v[202:205], v144 offset:53248
	ds_read_b128 v[206:209], v144 offset:54272
	ds_read_b128 v[210:213], v144 offset:55296
	ds_read_b128 v[214:217], v144 offset:56320
	s_waitcnt vmcnt(8)
	s_waitcnt lgkmcnt(0)
	s_barrier
	s_setprio 1
	v_mfma_f32_16x16x32_bf16 v[60:63], v[136:139], v[184:187], v[60:63]
	v_mfma_f32_16x16x32_bf16 v[56:59], v[152:155], v[184:187], v[56:59]
	v_mfma_f32_16x16x32_bf16 v[44:47], v[136:139], v[194:197], v[44:47]
	v_mfma_f32_16x16x32_bf16 v[40:43], v[152:155], v[194:197], v[40:43]
	v_mfma_f32_16x16x32_bf16 v[28:31], v[136:139], v[202:205], v[28:31]
	v_mfma_f32_16x16x32_bf16 v[24:27], v[152:155], v[202:205], v[24:27]
	v_mfma_f32_16x16x32_bf16 v[12:15], v[136:139], v[210:213], v[12:15]
	v_mfma_f32_16x16x32_bf16 v[8:11], v[152:155], v[210:213], v[8:11]
	v_mfma_f32_16x16x32_bf16 v[60:63], v[148:151], v[188:191], v[60:63]
	v_mfma_f32_16x16x32_bf16 v[56:59], v[156:159], v[188:191], v[56:59]
	v_mfma_f32_16x16x32_bf16 v[44:47], v[148:151], v[198:201], v[44:47]
	v_mfma_f32_16x16x32_bf16 v[40:43], v[156:159], v[198:201], v[40:43]
	v_mfma_f32_16x16x32_bf16 v[28:31], v[148:151], v[206:209], v[28:31]
	v_mfma_f32_16x16x32_bf16 v[24:27], v[156:159], v[206:209], v[24:27]
	v_mfma_f32_16x16x32_bf16 v[12:15], v[148:151], v[214:217], v[12:15]
	v_mfma_f32_16x16x32_bf16 v[8:11], v[156:159], v[214:217], v[8:11]
	s_setprio 0
	s_setprio 1
	v_mfma_f32_16x16x32_bf16 v[52:55], v[160:163], v[184:187], v[52:55]
	v_mfma_f32_16x16x32_bf16 v[48:51], v[168:171], v[184:187], v[48:51]
	v_mfma_f32_16x16x32_bf16 v[36:39], v[160:163], v[194:197], v[36:39]
	v_mfma_f32_16x16x32_bf16 v[32:35], v[168:171], v[194:197], v[32:35]
	v_mfma_f32_16x16x32_bf16 v[20:23], v[160:163], v[202:205], v[20:23]
	v_mfma_f32_16x16x32_bf16 v[16:19], v[168:171], v[202:205], v[16:19]
	v_mfma_f32_16x16x32_bf16 v[4:7], v[160:163], v[210:213], v[4:7]
	v_mfma_f32_16x16x32_bf16 v[0:3], v[168:171], v[210:213], v[0:3]
	v_mfma_f32_16x16x32_bf16 v[52:55], v[164:167], v[188:191], v[52:55]
	v_mfma_f32_16x16x32_bf16 v[48:51], v[180:183], v[188:191], v[48:51]
	v_mfma_f32_16x16x32_bf16 v[36:39], v[164:167], v[198:201], v[36:39]
	v_mfma_f32_16x16x32_bf16 v[32:35], v[180:183], v[198:201], v[32:35]
	v_mfma_f32_16x16x32_bf16 v[20:23], v[164:167], v[206:209], v[20:23]
	v_mfma_f32_16x16x32_bf16 v[16:19], v[180:183], v[206:209], v[16:19]
	v_mfma_f32_16x16x32_bf16 v[4:7], v[164:167], v[214:217], v[4:7]
	v_mfma_f32_16x16x32_bf16 v[0:3], v[180:183], v[214:217], v[0:3]
	s_setprio 0
	s_barrier
	s_add_i32 s64, s64, 2
	s_add_u32 s89, s89, 0x10000
	s_addc_u32 s90, s90, 0
	s_add_u32 s91, s91, 0x100
	s_addc_u32 s92, s92, 0
	s_cmpk_gt_u32 s64, 0xa9
	s_cbranch_scc0 .LBB0_935
	s_and_b64 vcc, exec, s[30:31]
	s_cbranch_vccz .LBB0_938
	s_barrier
